# speedup vs baseline: 1.0117x; 1.0117x over previous
; #define LAS __attribute__((address_space(3)))
; DI int obid() { int b = blockIdx.x; asm volatile("" : "+s"(b)); return b; }
; DI void phase_attn(const Params& P, LAS unsigned char* lds, bool dry) {
;     for (int item = obid(); item < 512; item += gridDim.x) {
;         const int h = item & 7, p = (item >> 3) & 31, b = item >> 8;
;         attn_unit(P, lds, b, h, 63 - p, dry);
; __global__ void __launch_bounds__(NTHR) fwd_megakernel(Params P) {
;     ...
;             case 23:
;     ...
;                 phase_attn(Q, lds, true);
;     ...
;                 phase_attn(Q, lds, false); break;
.LBB0_26:
	v_readlane_b32 s2, v245, 33
	s_cmp_gt_i32 s2, 22
	s_mov_b64 s[2:3], -1
	s_cbranch_scc0 .LBB0_73
	v_readlane_b32 s2, v245, 33
	s_cmp_eq_u32 s2, 23
	s_mov_b64 s[48:49], -1
	s_cbranch_scc0 .LBB0_72
	s_mov_b32 s54, s28
	s_cmpk_gt_i32 s54, 0x1ff
	s_movk_i32 s29, 0x190
	s_cbranch_scc1 .LBB0_71
	s_mov_b32 s55, s54
	v_mov_b32_e32 v248, 0xc00
	v_mov_b32_e32 v249, 0xff800000
	s_branch .LBB0_31

; #define LAS __attribute__((address_space(3)))
; DI int otid() { int t = threadIdx.x; asm volatile("" : "+v"(t)); return t; }
; DI unsigned char* ows(const Params& P) { unsigned char* p = P.ws; asm volatile("" : "+s"(p)); return p; }
; DI void attn_unit(const Params& P, LAS unsigned char* lds, int b, int h, int qb, bool dry) {
;     const int tid = otid(), lane = tid & 63, w = __builtin_amdgcn_readfirstlane(tid >> 6), r = lane & 31, hh = lane >> 5;
;     bf16_t* Q = (bf16_t*)(ows(P) + OFF_Q);
;     const bf16_t* KV = (const bf16_t*)(ows(P) + OFF_KV); const bf16_t* KPE = (const bf16_t*)(ows(P) + OFF_KPE); const bf16_t* VT = (const bf16_t*)(ows(P) + OFF_U);
;     LAS unsigned char* Ks = lds; LAS unsigned char* Vs = lds + 2 * KS_BYTES;
;     const int q0 = qb * 256 + w * 32;
;     bf16_t* qrow = Q + ((size_t)b * SEQ + q0 + r) * 1536 + h * 192;
;     bf16x8 qf[12];
; #pragma unroll
;     for (int s = 0; s < 12; ++s) qf[s] = *(const bf16x8*)(qrow + 16 * s + 8 * hh);
;     f32x16 o[4];
; #pragma unroll
;     for (int d = 0; d < 4; ++d)
; #pragma unroll
;         for (int i = 0; i < 16; ++i) o[d][i] = 0.f;
;     float mrun = -INFINITY, lrun = 0.f;
;     const int nt = 4 * (qb + 1);
;     const bf16_t* KVb = KV + (size_t)b * SEQ * 2048 + h * 256; const bf16_t* KPEb = KPE + (size_t)b * SEQ * 64; const bf16_t* VTb = VT + (size_t)(b * 8 + h) * 128 * SEQ;
;     const int kn_off = (tid >> 4) * 2048 + (tid & 15) * 8, kn_dst = (tid >> 4) * KS_STRIDE + (tid & 15) * 16;
;     const int kp_off = (tid >> 3) * 64 + (tid & 7) * 8, kp_dst = (tid >> 3) * KS_STRIDE + 256 + (tid & 7) * 16;
;     const int v_off = (tid >> 3) * SEQ + (tid & 7) * 8, v_dst = (tid >> 3) * VS_STRIDE + (tid & 7) * 16;
.LBB0_31:
	s_waitcnt vmcnt(0)
	v_mov_b32_e32 v2, v195
	s_load_dwordx8 s[64:71], s[84:85], 0xc8
	s_bfe_u32 s35, s55, 0x50003
	v_readfirstlane_b32 s49, v2
	s_xor_b32 s37, s35, 63
	s_ashr_i32 s3, s49, 1
	s_ashr_i32 s46, s55, 8
	s_lshl_b32 s2, s37, 8
	s_and_b32 s53, s3, 0xffffffe0
	s_and_b32 s48, s54, 7
	s_waitcnt lgkmcnt(0)
	s_mov_b64 s[60:61], s[64:65]
	s_add_i32 s53, s53, s2
	s_ashr_i32 s47, s46, 31
	s_lshl_b32 s52, s48, 9
	s_lshr_b32 s56, s55, 3
	s_and_b32 s42, s55, 7
	s_mov_b64 s[62:63], s[66:67]
	s_mov_b64 s[64:65], s[68:69]
	s_mov_b64 s[66:67], s[70:71]
	s_lshl_b64 s[2:3], s[46:47], 14
	s_ashr_i32 s20, s53, 31
	v_and_b32_e32 v23, 31, v2
	s_mov_b64 s[30:31], s[66:67]
	s_add_u32 s36, s2, s53
	v_or_b32_e32 v3, s36, v23
	v_mov_b64_e32 v[0:1], s[30:31]
	s_addc_u32 s20, s3, s20
	v_mad_u64_u32 v[0:1], s[30:31], v3, s39, v[0:1]
	s_mul_i32 s36, s42, 0xc0
	v_mad_i32_i24 v1, s20, v248, v1
	s_lshl_b32 s20, s36, 1
	s_lshl_b32 s62, s37, 2
	v_bfe_u32 v36, v2, 5, 1
	s_mov_b64 s[40:41], s[66:67]
	v_lshl_add_u64 v[0:1], v[0:1], 0, s[20:21]
	s_mov_b64 s[30:31], 0xd808000
	s_add_i32 s59, s62, 4
	s_lshl_b64 s[44:45], s[46:47], 26
	v_lshl_add_u64 v[186:187], v[0:1], 0, s[30:31]
	v_lshlrev_b32_e32 v184, 4, v36
	s_add_u32 s30, s40, s44
	s_mov_b64 s[26:27], s[66:67]
	s_mov_b64 s[50:51], s[66:67]
	v_lshl_add_u64 v[0:1], v[186:187], 0, v[184:185]
	s_addc_u32 s31, s41, s45
	s_lshl_b32 s37, s42, 8
	s_lshl_b32 s43, s42, 9
	v_and_b32_e32 v3, 15, v2
	global_load_dwordx4 v[96:99], v[0:1], off
	global_load_dwordx4 v[100:103], v[0:1], off offset:32
	global_load_dwordx4 v[104:107], v[0:1], off offset:64
	global_load_dwordx4 v[108:111], v[0:1], off offset:96
	global_load_dwordx4 v[112:115], v[0:1], off offset:128
	global_load_dwordx4 v[116:119], v[0:1], off offset:160
	global_load_dwordx4 v[120:123], v[0:1], off offset:192
	global_load_dwordx4 v[124:127], v[0:1], off offset:224
	global_load_dwordx4 v[128:131], v[0:1], off offset:256
	global_load_dwordx4 v[132:135], v[0:1], off offset:288
	global_load_dwordx4 v[136:139], v[0:1], off offset:320
	global_load_dwordx4 v[140:143], v[0:1], off offset:352
	s_add_u32 s80, s30, s43
	v_ashrrev_i32_e32 v1, 4, v2
	v_lshlrev_b32_e32 v0, 3, v3
	s_addc_u32 s81, s31, 0
	s_lshl_b32 s57, s46, 3
	v_lshl_or_b32 v0, v1, 11, v0
	v_mul_lo_u32 v1, v1, s29
	s_lshl_b64 s[30:31], s[46:47], 21
	s_or_b32 s46, s57, s42
	v_lshl_add_u32 v38, v3, 4, v1
	v_and_b32_e32 v1, 7, v2
	s_ashr_i32 s47, s46, 31
	v_ashrrev_i32_e32 v39, 3, v2
	v_lshlrev_b32_e32 v2, 3, v1
	v_lshlrev_b32_e32 v22, 4, v1
	v_ashrrev_i32_e32 v1, 31, v0
	s_lshl_b64 s[46:47], s[46:47], 22
	v_lshlrev_b64 v[0:1], 1, v[0:1]
	s_add_u32 s94, s50, s46
	v_lshl_add_u64 v[26:27], s[80:81], 0, v[0:1]
	s_mov_b32 s28, 0x13808000
	s_addc_u32 s95, s51, s47
	v_lshl_or_b32 v10, v39, 6, v2
	v_lshl_or_b32 v14, v39, 14, v2
	v_add_co_u32_e32 v2, vcc, s28, v26
	s_mov_b32 s28, 0x13828000
	s_nop 0
	v_addc_co_u32_e32 v3, vcc, 0, v27, vcc
	s_add_u32 s26, s26, s30
	v_add_co_u32_e32 v6, vcc, s28, v26
	v_ashrrev_i32_e32 v11, 31, v10
	s_addc_u32 s27, s27, s31
	v_ashrrev_i32_e32 v15, 31, v14
	v_addc_co_u32_e32 v7, vcc, 0, v27, vcc
	v_lshl_add_u64 v[28:29], v[10:11], 1, s[26:27]
	s_mov_b32 s26, 0xd408000
	v_lshlrev_b64 v[30:31], 1, v[14:15]
	v_add_co_u32_e32 v10, vcc, s26, v28
	v_lshl_add_u64 v[18:19], s[94:95], 0, v[30:31]
	s_mov_b64 s[26:27], 0x5808000
	v_addc_co_u32_e32 v11, vcc, 0, v29, vcc
	v_lshl_add_u64 v[32:33], v[18:19], 0, s[26:27]
	s_mov_b32 s26, 0x5808000
	v_add_co_u32_e32 v14, vcc, s26, v18
	global_load_dwordx4 v[2:5], v[2:3], off
	s_nop 0
	v_addc_co_u32_e32 v15, vcc, 0, v19, vcc
	s_mov_b32 s26, 0x5a08000
	global_load_dwordx4 v[6:9], v[6:7], off
	v_add_co_u32_e32 v34, vcc, s26, v18
	global_load_dwordx4 v[10:13], v[10:11], off
	s_nop 0
	v_addc_co_u32_e32 v35, vcc, 0, v19, vcc
	global_load_dwordx4 v[14:17], v[14:15], off
	s_movk_i32 s68, 0x88
	global_load_dwordx4 v[18:21], v[34:35], off
	v_mad_u64_u32 v[24:25], s[96:97], v39, s68, v[22:23]
	v_add_u32_e32 v250, 0, v38
	s_movk_i32 s26, 0x108
	s_waitcnt lgkmcnt(0)
	s_barrier
; #define ATT_LOAD(kr, vr, t) do { const bf16_t* kp_ = KVb + (size_t)(t) * 64 * 2048 + kn_off; \
;         kr[0] = *(const u32x4*)kp_; kr[1] = *(const u32x4*)(kp_ + 32 * 2048); kr[2] = *(const u32x4*)(KPEb + (t) * 64 * 64 + kp_off); \
;         const bf16_t* vp_ = VTb + (t) * 64 + v_off; vr[0] = *(const u32x4*)vp_; vr[1] = *(const u32x4*)(vp_ + 64 * SEQ); } while (0)
; DI void attn_unit(const Params& P, LAS unsigned char* lds, int b, int h, int qb, bool dry) {
;     ...
;     f32x16 o[4];
; #pragma unroll
;     for (int d = 0; d < 4; ++d)
; #pragma unroll
;         for (int i = 0; i < 16; ++i) o[d][i] = 0.f;
;     float mrun = -INFINITY, lrun = 0.f;
;     ...
;     ATT_LOAD(kA, vA, 0);
;     __syncthreads();
;     ATT_STORE(kA, vA, 0);
;     ATT_LOAD(kA, vA, 1);
;     __syncthreads();
	s_waitcnt vmcnt(0)
	ds_write_b128 v250, v[2:5]
	ds_write_b128 v250, v[6:9] offset:12800
	v_mad_u64_u32 v[2:3], s[26:27], v39, s26, v[24:25]
	v_add_u32_e32 v252, 0, v24
	s_mov_b32 s26, 0x13848000
	v_add_u32_e32 v251, 0, v2
	v_add_u32_e32 v253, 0xc800, v252
	v_add_u32_e32 v254, 0xea00, v252
	v_add_co_u32_e32 v2, vcc, s26, v26
	ds_write_b128 v251, v[10:13] offset:256
	ds_write2_b64 v253, v[14:15], v[16:17] offset1:1
	ds_write2_b64 v254, v[18:19], v[20:21] offset1:1
	v_addc_co_u32_e32 v3, vcc, 0, v27, vcc
	s_mov_b32 s26, 0x13868000
	global_load_dwordx4 v[144:147], v[2:3], off
	v_add_co_u32_e32 v2, vcc, s26, v26
	s_mov_b32 s26, 0xd40a000
	s_nop 0
	v_addc_co_u32_e32 v3, vcc, 0, v27, vcc
	global_load_dwordx4 v[148:151], v[2:3], off
	v_add_co_u32_e32 v2, vcc, s26, v28
	s_or_b32 s48, s57, s48
	s_nop 0
	v_addc_co_u32_e32 v3, vcc, 0, v29, vcc
	global_load_dwordx4 v[152:155], v[2:3], off
	global_load_dwordx4 v[156:159], v[32:33], off offset:128
	global_load_dwordx4 v[160:163], v[34:35], off offset:128
	s_ashr_i32 s26, s49, 7
	s_ashr_i32 s49, s48, 31
	s_lshl_b64 s[48:49], s[48:49], 22
	s_add_u32 s50, s50, s48
	v_mad_u32_u24 v213, v23, s29, 0
	s_movk_i32 s27, 0xfef8
	s_addc_u32 s51, s51, s49
	s_or_b32 s57, s44, s52
	v_mad_i32_i24 v18, v23, s27, v213
	v_readlane_b32 s27, v246, 47
	s_add_u32 s40, s40, s57
	v_mad_u64_u32 v[16:17], s[80:81], v39, s29, v[22:23]
	v_mov_b32_e32 v2, s27
	s_mov_b64 s[42:43], 0xd40e000
	s_addc_u32 s41, s41, s45
	v_lshlrev_b32_e32 v37, 3, v36
	v_readlane_b32 s96, v246, 55
	v_mad_u32_u24 v17, v23, s68, v2
	v_lshl_add_u64 v[188:189], v[28:29], 0, s[42:43]
	v_lshl_add_u64 v[2:3], s[50:51], 0, v[30:31]
	s_mov_b64 s[42:43], 0x5a08180
	v_lshl_add_u64 v[0:1], s[40:41], 0, v[0:1]
	s_mov_b64 s[40:41], 0x138e8000
	v_mov_b32_e32 v14, v185
	v_mov_b32_e32 v15, v185
	v_readlane_b32 s97, v246, 56
	v_readlane_b32 s94, v246, 63
	v_or_b32_e32 v214, s53, v23
	v_lshlrev_b32_e32 v212, 2, v36
	v_lshl_add_u64 v[190:191], v[2:3], 0, s[42:43]
	v_lshl_add_u64 v[192:193], v[0:1], 0, s[40:41]
	s_add_i32 s40, s26, s62
	v_mov_b32_e32 v0, v185
	v_mov_b32_e32 v1, v185
	v_mov_b32_e32 v2, v185
	v_mov_b32_e32 v3, v185
	v_mov_b32_e32 v4, v185
	v_mov_b32_e32 v5, v185
	v_mov_b32_e32 v6, v185
	v_mov_b32_e32 v7, v185
	v_mov_b32_e32 v8, v185
	v_mov_b32_e32 v9, v185
	v_mov_b32_e32 v10, v185
	v_mov_b32_e32 v11, v185
	v_mov_b32_e32 v12, v185
	v_mov_b32_e32 v13, v185
	v_add_u32_e32 v216, v18, v37
	v_add_u32_e32 v217, 0, v16
	v_add_u32_e32 v218, v17, v37
	v_mov_b64_e32 v[30:31], v[14:15]
	v_mov_b64_e32 v[46:47], v[14:15]
	v_mov_b64_e32 v[62:63], v[14:15]
	s_mov_b32 s20, 2
	v_readlane_b32 s98, v246, 57
	v_readlane_b32 s95, v245, 0
	v_readlane_b32 s71, v246, 62
	v_readlane_b32 s69, v246, 61
	s_mov_b32 s81, 0x14000
	v_readlane_b32 s28, v246, 54
	s_mov_b32 s58, s45
	s_sub_i32 s27, 1, s40
	s_sub_i32 s62, 0, s62
	s_sub_i32 s63, 0, s40
	v_mov_b32_e32 v194, 0xff800000
	v_mov_b32_e32 v196, 0
	v_mov_b32_e32 v197, 0
	v_mov_b32_e32 v198, 0
	v_mov_b32_e32 v199, 0
	v_mov_b32_e32 v200, 0
	v_mov_b32_e32 v201, 0
	v_mov_b32_e32 v202, 0
	v_mov_b32_e32 v203, 0
	v_mov_b32_e32 v204, 0
	v_mov_b32_e32 v205, 0
	v_mov_b32_e32 v206, 0
	v_mov_b32_e32 v207, 0
	v_mov_b32_e32 v208, 0
	v_mov_b32_e32 v209, 0
	v_mov_b32_e32 v210, 0
	v_mov_b32_e32 v211, 0
	v_mov_b32_e32 v215, 0
	v_mov_b32_e32 v219, v212
	v_mov_b64_e32 v[28:29], v[12:13]
	v_mov_b64_e32 v[26:27], v[10:11]
	v_mov_b64_e32 v[24:25], v[8:9]
	v_mov_b64_e32 v[22:23], v[6:7]
	v_mov_b64_e32 v[20:21], v[4:5]
	v_mov_b64_e32 v[18:19], v[2:3]
	v_mov_b64_e32 v[16:17], v[0:1]
	v_mov_b64_e32 v[44:45], v[12:13]
	v_mov_b64_e32 v[42:43], v[10:11]
	v_mov_b64_e32 v[40:41], v[8:9]
	v_mov_b64_e32 v[38:39], v[6:7]
	v_mov_b64_e32 v[36:37], v[4:5]
	v_mov_b64_e32 v[34:35], v[2:3]
	v_mov_b64_e32 v[32:33], v[0:1]
	v_mov_b64_e32 v[60:61], v[12:13]
	v_mov_b64_e32 v[58:59], v[10:11]
	v_mov_b64_e32 v[56:57], v[8:9]
	v_mov_b64_e32 v[54:55], v[6:7]
	v_mov_b64_e32 v[52:53], v[4:5]
	v_mov_b64_e32 v[50:51], v[2:3]
	v_mov_b64_e32 v[48:49], v[0:1]
	s_mov_b64 s[96:97], 0x4000
	v_readlane_b32 s99, v246, 58
	s_waitcnt lgkmcnt(0)
	s_barrier
	s_branch .LBB0_33

; #define LAS __attribute__((address_space(3)))
; #define MFMA32(a, b, c) __builtin_amdgcn_mfma_f32_32x32x16_bf16((a), (b), (c), 0, 0, 0)
; DI void attn_unit(const Params& P, LAS unsigned char* lds, int b, int h, int qb, bool dry) {
;     ...
;     auto qk_softmax = [&](int kt, int kslot, bool domask) {
;         const LAS unsigned char* kb_ = Ks + kslot * KS_BYTES + r * KS_STRIDE + 16 * hh;
;         f32x16 s0, s1;
;         __builtin_amdgcn_s_setprio(1);
;         { const f32x16 z16 = {0.f, 0.f, 0.f, 0.f, 0.f, 0.f, 0.f, 0.f, 0.f, 0.f, 0.f, 0.f, 0.f, 0.f, 0.f, 0.f};
;           const bf16x8 a0 = *(const LAS bf16x8*)(kb_), a1 = *(const LAS bf16x8*)(kb_ + 32 * KS_STRIDE);
;           s0 = MFMA32(a0, qf[0], z16); s1 = MFMA32(a1, qf[0], z16); }
; #pragma unroll
;         for (int s = 1; s < 12; ++s) {
;             const bf16x8 a0 = *(const LAS bf16x8*)(kb_ + 32 * s), a1 = *(const LAS bf16x8*)(kb_ + 32 * KS_STRIDE + 32 * s);
;             s0 = MFMA32(a0, qf[s], s0); s1 = MFMA32(a1, qf[s], s1);
;         }
;         __builtin_amdgcn_s_setprio(0);
.LBB0_35:
	s_add_i32 s80, s62, s20
	s_add_i32 s40, s80, -2
	s_cmp_gt_i32 s40, s26
	v_add_u32_e32 v220, v213, v184
	s_cbranch_scc1 .LBB0_41
	s_add_i32 s40, s63, s20
	s_cmp_lg_u32 s40, 2
	s_setprio 1
	ds_read_b128 v[222:225], v220
	ds_read_b128 v[226:229], v220 offset:12800
	ds_read_b128 v[230:233], v220 offset:32
	ds_read_b128 v[234:237], v220 offset:12832
	s_waitcnt lgkmcnt(3)
	v_mfma_f32_32x32x16_bf16 v[80:95], v[222:225], v[96:99], v[196:211]
	ds_read_b128 v[222:225], v220 offset:64
	s_waitcnt lgkmcnt(3)
	v_mfma_f32_32x32x16_bf16 v[64:79], v[226:229], v[96:99], v[196:211]
	ds_read_b128 v[226:229], v220 offset:12864
	s_waitcnt lgkmcnt(3)
	v_mfma_f32_32x32x16_bf16 v[80:95], v[230:233], v[100:103], v[80:95]
	ds_read_b128 v[230:233], v220 offset:96
	s_waitcnt lgkmcnt(3)
	v_mfma_f32_32x32x16_bf16 v[64:79], v[234:237], v[100:103], v[64:79]
	ds_read_b128 v[234:237], v220 offset:12896
	s_waitcnt lgkmcnt(3)
	v_mfma_f32_32x32x16_bf16 v[80:95], v[222:225], v[104:107], v[80:95]
	ds_read_b128 v[222:225], v220 offset:128
	s_waitcnt lgkmcnt(3)
	v_mfma_f32_32x32x16_bf16 v[64:79], v[226:229], v[104:107], v[64:79]
	ds_read_b128 v[226:229], v220 offset:12928
	s_waitcnt lgkmcnt(3)
	v_mfma_f32_32x32x16_bf16 v[80:95], v[230:233], v[108:111], v[80:95]
	ds_read_b128 v[230:233], v220 offset:160
	s_waitcnt lgkmcnt(3)
	v_mfma_f32_32x32x16_bf16 v[64:79], v[234:237], v[108:111], v[64:79]
	ds_read_b128 v[234:237], v220 offset:12960
	s_waitcnt lgkmcnt(3)
	v_mfma_f32_32x32x16_bf16 v[80:95], v[222:225], v[112:115], v[80:95]
	ds_read_b128 v[222:225], v220 offset:192
	s_waitcnt lgkmcnt(3)
	v_mfma_f32_32x32x16_bf16 v[64:79], v[226:229], v[112:115], v[64:79]
	ds_read_b128 v[226:229], v220 offset:12992
	s_waitcnt lgkmcnt(3)
	v_mfma_f32_32x32x16_bf16 v[80:95], v[230:233], v[116:119], v[80:95]
	ds_read_b128 v[230:233], v220 offset:224
	s_waitcnt lgkmcnt(3)
	v_mfma_f32_32x32x16_bf16 v[64:79], v[234:237], v[116:119], v[64:79]
	ds_read_b128 v[234:237], v220 offset:13024
	s_waitcnt lgkmcnt(3)
	v_mfma_f32_32x32x16_bf16 v[80:95], v[222:225], v[120:123], v[80:95]
	ds_read_b128 v[222:225], v220 offset:256
	s_waitcnt lgkmcnt(3)
	v_mfma_f32_32x32x16_bf16 v[64:79], v[226:229], v[120:123], v[64:79]
	ds_read_b128 v[226:229], v220 offset:13056
	s_waitcnt lgkmcnt(3)
	v_mfma_f32_32x32x16_bf16 v[80:95], v[230:233], v[124:127], v[80:95]
	ds_read_b128 v[230:233], v220 offset:288
	s_waitcnt lgkmcnt(3)
	v_mfma_f32_32x32x16_bf16 v[64:79], v[234:237], v[124:127], v[64:79]
	ds_read_b128 v[234:237], v220 offset:13088
	s_waitcnt lgkmcnt(3)
	v_mfma_f32_32x32x16_bf16 v[80:95], v[222:225], v[128:131], v[80:95]
	ds_read_b128 v[222:225], v220 offset:320
	s_waitcnt lgkmcnt(3)
	v_mfma_f32_32x32x16_bf16 v[64:79], v[226:229], v[128:131], v[64:79]
	ds_read_b128 v[226:229], v220 offset:13120
	s_waitcnt lgkmcnt(3)
	v_mfma_f32_32x32x16_bf16 v[80:95], v[230:233], v[132:135], v[80:95]
	ds_read_b128 v[230:233], v220 offset:352
	s_waitcnt lgkmcnt(3)
	v_mfma_f32_32x32x16_bf16 v[64:79], v[234:237], v[132:135], v[64:79]
	ds_read_b128 v[234:237], v220 offset:13152
	s_waitcnt lgkmcnt(3)
	v_mfma_f32_32x32x16_bf16 v[80:95], v[222:225], v[136:139], v[80:95]
	s_waitcnt lgkmcnt(2)
	v_mfma_f32_32x32x16_bf16 v[64:79], v[226:229], v[136:139], v[64:79]
	s_waitcnt lgkmcnt(1)
	v_mfma_f32_32x32x16_bf16 v[80:95], v[230:233], v[140:143], v[80:95]
	s_waitcnt lgkmcnt(0)
	v_mfma_f32_32x32x16_bf16 v[64:79], v[234:237], v[140:143], v[64:79]
	s_setprio 0
	s_nop 0
	s_mov_b64 vcc, s[52:53]
	s_cbranch_vccnz .Lattn_hw0_v5
	s_waitcnt vmcnt(0)
	s_branch .Lattn_hw0_go

; DI void attn_unit(const Params& P, LAS unsigned char* lds, int b, int h, int qb, bool dry) {
;     ...
;         if (domask) {
;             const int qg = q0 + r, kbase = 64 * kt + 4 * hh;
; #pragma unroll
;             for (int i = 0; i < 16; ++i) { const int kk = kbase + (i & 3) + 8 * (i >> 2);
;                 if (kk > qg) s0[i] = -INFINITY;
;                 if (kk + 32 > qg) s1[i] = -INFINITY; }
;         }
;         float mx = fmaxf(fmaxf(s0[0], s0[1]), s0[2]);
; #pragma unroll
;         for (int i = 3; i < 15; i += 2) mx = fmaxf(fmaxf(mx, s0[i]), s0[i + 1]);
;         mx = fmaxf(fmaxf(mx, s0[15]), s1[0]);
; #pragma unroll
;         for (int i = 1; i < 15; i += 2) mx = fmaxf(fmaxf(mx, s1[i]), s1[i + 1]);
;         mx = fmaxf(mx, s1[15]);
;         { const auto rr = __builtin_amdgcn_permlane32_swap(__float_as_uint(mx), __float_as_uint(mx), false, false);
;           mx = fmaxf(__uint_as_float(rr[0]), __uint_as_float(rr[1])); }
;         if (__builtin_amdgcn_ballot_w64(mx > mrun + 8.f)) {
.Lattn_hw0_go:
	v_add_u32_e32 v238, 0x10c00, v252
	ds_write_b128 v250, v[144:147] offset:25600
	ds_write_b128 v250, v[148:151] offset:38400
	ds_write_b128 v217, v[152:155] offset:25856
	ds_write2_b64 v238, v[156:157], v[158:159] offset1:1
	v_add_u32_e32 v238, 0x2200, v238
	ds_write2_b64 v238, v[160:161], v[162:163] offset1:1
	s_cbranch_scc1 .LBB0_38
	v_add_u32_e32 v221, 32, v219
	v_cmp_le_i32_e32 vcc, v221, v214
	v_add_u32_e32 v221, 33, v219
	s_nop 6
	v_cndmask_b32_e32 v64, v249, v64, vcc
	v_cmp_lt_i32_e32 vcc, v219, v214
	s_nop 1
	v_cndmask_b32_e32 v81, v249, v81, vcc
	v_cmp_le_i32_e32 vcc, v219, v214
	s_nop 1
	v_cndmask_b32_e32 v80, v249, v80, vcc
	v_cmp_le_i32_e32 vcc, v221, v214
	v_add_u32_e32 v221, 2, v219
	s_nop 0
	v_cndmask_b32_e32 v65, v249, v65, vcc
	v_cmp_le_i32_e32 vcc, v221, v214
	v_add_u32_e32 v221, 34, v219
	s_nop 0
	v_cndmask_b32_e32 v82, v249, v82, vcc
	v_cmp_le_i32_e32 vcc, v221, v214
	v_add_u32_e32 v221, 3, v219
	s_nop 0
	v_cndmask_b32_e32 v66, v249, v66, vcc
	v_cmp_le_i32_e32 vcc, v221, v214
	v_add_u32_e32 v221, 35, v219
	s_nop 0
	v_cndmask_b32_e32 v83, v249, v83, vcc
	v_cmp_le_i32_e32 vcc, v221, v214
	v_add_u32_e32 v221, 8, v219
	s_nop 0
	v_cndmask_b32_e32 v67, v249, v67, vcc
	v_cmp_le_i32_e32 vcc, v221, v214
	v_add_u32_e32 v221, 40, v219
	s_nop 0
	v_cndmask_b32_e32 v84, v249, v84, vcc
	v_cmp_le_i32_e32 vcc, v221, v214
	v_add_u32_e32 v221, 9, v219
	s_nop 0
	v_cndmask_b32_e32 v68, v249, v68, vcc
	v_cmp_le_i32_e32 vcc, v221, v214
	v_add_u32_e32 v221, 41, v219
	s_nop 0
	v_cndmask_b32_e32 v85, v249, v85, vcc
	v_cmp_le_i32_e32 vcc, v221, v214
	v_add_u32_e32 v221, 10, v219
	s_nop 0
	v_cndmask_b32_e32 v69, v249, v69, vcc
	v_cmp_le_i32_e32 vcc, v221, v214
	v_add_u32_e32 v221, 42, v219
	s_nop 0
	v_cndmask_b32_e32 v86, v249, v86, vcc
	v_cmp_le_i32_e32 vcc, v221, v214
	v_add_u32_e32 v221, 11, v219
	s_nop 0
	v_cndmask_b32_e32 v70, v249, v70, vcc
	v_cmp_le_i32_e32 vcc, v221, v214
	v_add_u32_e32 v221, 43, v219
	s_nop 0
	v_cndmask_b32_e32 v87, v249, v87, vcc
	v_cmp_le_i32_e32 vcc, v221, v214
	v_add_u32_e32 v221, 16, v219
	s_nop 0
	v_cndmask_b32_e32 v71, v249, v71, vcc
	v_cmp_le_i32_e32 vcc, v221, v214
	v_add_u32_e32 v221, 48, v219
	s_nop 0
	v_cndmask_b32_e32 v88, v249, v88, vcc
	v_cmp_le_i32_e32 vcc, v221, v214
	v_add_u32_e32 v221, 17, v219
	s_nop 0
	v_cndmask_b32_e32 v72, v249, v72, vcc
	v_cmp_le_i32_e32 vcc, v221, v214
	v_add_u32_e32 v221, 49, v219
	s_nop 0
	v_cndmask_b32_e32 v89, v249, v89, vcc
	v_cmp_le_i32_e32 vcc, v221, v214
	v_add_u32_e32 v221, 18, v219
	s_nop 0
	v_cndmask_b32_e32 v73, v249, v73, vcc
	v_cmp_le_i32_e32 vcc, v221, v214
	v_add_u32_e32 v221, 50, v219
	s_nop 0
	v_cndmask_b32_e32 v90, v249, v90, vcc
	v_cmp_le_i32_e32 vcc, v221, v214
	v_add_u32_e32 v221, 19, v219
	s_nop 0
	v_cndmask_b32_e32 v74, v249, v74, vcc
	v_cmp_le_i32_e32 vcc, v221, v214
	v_add_u32_e32 v221, 51, v219
	s_nop 0
	v_cndmask_b32_e32 v91, v249, v91, vcc
	v_cmp_le_i32_e32 vcc, v221, v214
	v_add_u32_e32 v221, 24, v219
	s_nop 0
	v_cndmask_b32_e32 v75, v249, v75, vcc
	v_cmp_le_i32_e32 vcc, v221, v214
	v_add_u32_e32 v221, 56, v219
	s_nop 0
	v_cndmask_b32_e32 v92, v249, v92, vcc
	v_cmp_le_i32_e32 vcc, v221, v214
	v_add_u32_e32 v221, 25, v219
	s_nop 0
	v_cndmask_b32_e32 v76, v249, v76, vcc
	v_cmp_le_i32_e32 vcc, v221, v214
	v_add_u32_e32 v221, 57, v219
	s_nop 0
	v_cndmask_b32_e32 v93, v249, v93, vcc
	v_cmp_le_i32_e32 vcc, v221, v214
	v_add_u32_e32 v221, 26, v219
	s_nop 0
	v_cndmask_b32_e32 v77, v249, v77, vcc
	v_cmp_le_i32_e32 vcc, v221, v214
	v_add_u32_e32 v221, 58, v219
	s_nop 0
	v_cndmask_b32_e32 v94, v249, v94, vcc
	v_cmp_le_i32_e32 vcc, v221, v214
	v_add_u32_e32 v221, 27, v219
	s_nop 0
	v_cndmask_b32_e32 v78, v249, v78, vcc
	v_cmp_le_i32_e32 vcc, v221, v214
	v_add_u32_e32 v221, 59, v219
	s_nop 0
	v_cndmask_b32_e32 v95, v249, v95, vcc
	v_cmp_le_i32_e32 vcc, v221, v214
	s_nop 1
	v_cndmask_b32_e32 v79, v249, v79, vcc
.LBB0_38:
	s_nop 6
	v_max_f32_e32 v221, v81, v81
	v_max_f32_e32 v222, v80, v80
	v_max_f32_e32 v221, v222, v221
	v_max3_f32 v221, v221, v82, v83
	v_max3_f32 v221, v221, v84, v85
	v_max3_f32 v221, v221, v86, v87
	v_max3_f32 v221, v221, v88, v89
	v_max3_f32 v221, v221, v90, v91
	v_max3_f32 v221, v221, v92, v93
	v_max3_f32 v221, v221, v94, v95
	v_max3_f32 v221, v221, v64, v65
	v_max3_f32 v221, v221, v66, v67
	v_max3_f32 v221, v221, v68, v69
	v_max3_f32 v221, v221, v70, v71
	v_max3_f32 v221, v221, v72, v73
	v_max3_f32 v221, v221, v74, v75
	v_max3_f32 v221, v221, v76, v77
	v_max3_f32 v221, v221, v78, v79
	v_mov_b32_e32 v222, v221
	s_nop 1
	v_permlane32_swap_b32_e32 v221, v222
	v_max_f32_e32 v222, v222, v222
	v_max_f32_e32 v221, v221, v221
	v_max_f32_e32 v221, v221, v222
	v_cmp_lt_f32_e32 vcc, 0x41000000, v221
	s_cmp_eq_u32 s20, 2
	s_cbranch_scc1 .Lfold_r0
	s_cbranch_vccz .LBB0_40
; DI void attn_unit(const Params& P, LAS unsigned char* lds, int b, int h, int qb, bool dry) {
;     ...
;         if (__builtin_amdgcn_ballot_w64(mx > mrun + 8.f)) {
;             const float mnew = fmaxf(mrun, mx);
;             const float alpha = __builtin_amdgcn_exp2f(mrun - mnew);
;             mrun = mnew; lrun *= alpha;
; #pragma unroll
;             for (int d = 0; d < 4; ++d) o[d] = o[d] * alpha;
;         }
.Lfold_r0:
	v_max_f32_e32 v222, 0, v221
	s_cmp_eq_u32 s20, 2
	s_cselect_b64 vcc, -1, 0
	v_cndmask_b32_e32 v222, v222, v221, vcc
	v_sub_f32_e32 v194, 0, v222
	v_exp_f32_e32 v194, v194
	s_nop 0
	v_cndmask_b32_e32 v194, v194, v185, vcc
	v_mul_f32_e32 v215, v215, v194
	v_pk_mul_f32 v[62:63], v[62:63], v[194:195] op_sel_hi:[1,0]
	v_pk_mul_f32 v[60:61], v[60:61], v[194:195] op_sel_hi:[1,0]
	v_pk_mul_f32 v[58:59], v[58:59], v[194:195] op_sel_hi:[1,0]
	v_pk_mul_f32 v[56:57], v[56:57], v[194:195] op_sel_hi:[1,0]
	v_pk_mul_f32 v[54:55], v[54:55], v[194:195] op_sel_hi:[1,0]
	v_pk_mul_f32 v[52:53], v[52:53], v[194:195] op_sel_hi:[1,0]
	v_pk_mul_f32 v[50:51], v[50:51], v[194:195] op_sel_hi:[1,0]
	v_pk_mul_f32 v[48:49], v[48:49], v[194:195] op_sel_hi:[1,0]
	v_pk_mul_f32 v[46:47], v[46:47], v[194:195] op_sel_hi:[1,0]
	v_pk_mul_f32 v[44:45], v[44:45], v[194:195] op_sel_hi:[1,0]
	v_pk_mul_f32 v[42:43], v[42:43], v[194:195] op_sel_hi:[1,0]
	v_pk_mul_f32 v[40:41], v[40:41], v[194:195] op_sel_hi:[1,0]
	v_pk_mul_f32 v[38:39], v[38:39], v[194:195] op_sel_hi:[1,0]
	v_pk_mul_f32 v[36:37], v[36:37], v[194:195] op_sel_hi:[1,0]
	v_pk_mul_f32 v[34:35], v[34:35], v[194:195] op_sel_hi:[1,0]
	v_pk_mul_f32 v[32:33], v[32:33], v[194:195] op_sel_hi:[1,0]
	v_pk_mul_f32 v[30:31], v[30:31], v[194:195] op_sel_hi:[1,0]
	v_pk_mul_f32 v[28:29], v[28:29], v[194:195] op_sel_hi:[1,0]
	v_pk_mul_f32 v[26:27], v[26:27], v[194:195] op_sel_hi:[1,0]
	v_pk_mul_f32 v[24:25], v[24:25], v[194:195] op_sel_hi:[1,0]
	v_pk_mul_f32 v[22:23], v[22:23], v[194:195] op_sel_hi:[1,0]
	v_pk_mul_f32 v[20:21], v[20:21], v[194:195] op_sel_hi:[1,0]
	v_pk_mul_f32 v[18:19], v[18:19], v[194:195] op_sel_hi:[1,0]
	v_pk_mul_f32 v[16:17], v[16:17], v[194:195] op_sel_hi:[1,0]
	v_pk_mul_f32 v[14:15], v[14:15], v[194:195] op_sel_hi:[1,0]
	v_pk_mul_f32 v[12:13], v[12:13], v[194:195] op_sel_hi:[1,0]
	v_pk_mul_f32 v[10:11], v[10:11], v[194:195] op_sel_hi:[1,0]
	v_pk_mul_f32 v[8:9], v[8:9], v[194:195] op_sel_hi:[1,0]
	v_pk_mul_f32 v[6:7], v[6:7], v[194:195] op_sel_hi:[1,0]
	v_pk_mul_f32 v[4:5], v[4:5], v[194:195] op_sel_hi:[1,0]
	v_pk_mul_f32 v[2:3], v[2:3], v[194:195] op_sel_hi:[1,0]
	v_pk_mul_f32 v[0:1], v[0:1], v[194:195] op_sel_hi:[1,0]
	v_sub_f32_e32 v196, v196, v222
	v_sub_f32_e32 v197, v197, v222
	v_sub_f32_e32 v198, v198, v222
	v_sub_f32_e32 v199, v199, v222
	v_sub_f32_e32 v200, v200, v222
	v_sub_f32_e32 v201, v201, v222
	v_sub_f32_e32 v202, v202, v222
	v_sub_f32_e32 v203, v203, v222
	v_sub_f32_e32 v204, v204, v222
	v_sub_f32_e32 v205, v205, v222
	v_sub_f32_e32 v206, v206, v222
	v_sub_f32_e32 v207, v207, v222
	v_sub_f32_e32 v208, v208, v222
	v_sub_f32_e32 v209, v209, v222
	v_sub_f32_e32 v210, v210, v222
	v_sub_f32_e32 v211, v211, v222
	v_sub_f32_e32 v64, v64, v222
	v_sub_f32_e32 v65, v65, v222
	v_sub_f32_e32 v66, v66, v222
	v_sub_f32_e32 v67, v67, v222
	v_sub_f32_e32 v68, v68, v222
	v_sub_f32_e32 v69, v69, v222
	v_sub_f32_e32 v70, v70, v222
	v_sub_f32_e32 v71, v71, v222
	v_sub_f32_e32 v72, v72, v222
	v_sub_f32_e32 v73, v73, v222
	v_sub_f32_e32 v74, v74, v222
	v_sub_f32_e32 v75, v75, v222
	v_sub_f32_e32 v76, v76, v222
	v_sub_f32_e32 v77, v77, v222
	v_sub_f32_e32 v78, v78, v222
	v_sub_f32_e32 v79, v79, v222
	v_sub_f32_e32 v80, v80, v222
	v_sub_f32_e32 v81, v81, v222
	v_sub_f32_e32 v82, v82, v222
	v_sub_f32_e32 v83, v83, v222
	v_sub_f32_e32 v84, v84, v222
	v_sub_f32_e32 v85, v85, v222
	v_sub_f32_e32 v86, v86, v222
	v_sub_f32_e32 v87, v87, v222
	v_sub_f32_e32 v88, v88, v222
	v_sub_f32_e32 v89, v89, v222
	v_sub_f32_e32 v90, v90, v222
	v_sub_f32_e32 v91, v91, v222
	v_sub_f32_e32 v92, v92, v222
	v_sub_f32_e32 v93, v93, v222
	v_sub_f32_e32 v94, v94, v222
	v_sub_f32_e32 v95, v95, v222
; #define LAS __attribute__((address_space(3)))
; DI unsigned pk_bf16(float lo, float hi) { unsigned r; asm("v_cvt_pk_bf16_f32 %0, %1, %2" : "=v"(r) : "v"(lo), "v"(hi)); return r; }
; #define MFMA32(a, b, c) __builtin_amdgcn_mfma_f32_32x32x16_bf16((a), (b), (c), 0, 0, 0)
; DI bf16x8 cat4(s16x4 lo, s16x4 hi) { return __builtin_shufflevector(lo, hi, 0, 1, 2, 3, 4, 5, 6, 7); }
; DI void attn_unit(const Params& P, LAS unsigned char* lds, int b, int h, int qb, bool dry) {
;     ...
;         typedef float f32x2_ __attribute__((ext_vector_type(2)));
;         f32x2_ ls2 = {0.f, 0.f};
;         const f32x2_ m2 = {mrun, mrun};
; #pragma unroll
;         for (int i = 0; i < 16; i += 2) {
;             f32x2_ t = (f32x2_){s0[i], s0[i + 1]} - m2; t.x = __builtin_amdgcn_exp2f(t.x); t.y = __builtin_amdgcn_exp2f(t.y); ls2 += t; s0[i] = t.x; s0[i + 1] = t.y;
;             f32x2_ u = (f32x2_){s1[i], s1[i + 1]} - m2; u.x = __builtin_amdgcn_exp2f(u.x); u.y = __builtin_amdgcn_exp2f(u.y); ls2 += u; s1[i] = u.x; s1[i + 1] = u.y;
;         }
;         lrun += ls2.x + ls2.y;
; #pragma unroll
;         for (int s2 = 0; s2 < 2; ++s2) {
;             u32x4 t0, t1;
;             t0.x = pk_bf16(s0[8 * s2 + 0], s0[8 * s2 + 1]); t0.y = pk_bf16(s0[8 * s2 + 2], s0[8 * s2 + 3]); t0.z = pk_bf16(s0[8 * s2 + 4], s0[8 * s2 + 5]); t0.w = pk_bf16(s0[8 * s2 + 6], s0[8 * s2 + 7]);
;             t1.x = pk_bf16(s1[8 * s2 + 0], s1[8 * s2 + 1]); t1.y = pk_bf16(s1[8 * s2 + 2], s1[8 * s2 + 3]); t1.z = pk_bf16(s1[8 * s2 + 4], s1[8 * s2 + 5]); t1.w = pk_bf16(s1[8 * s2 + 6], s1[8 * s2 + 7]);
;             pf[0][s2] = __builtin_bit_cast(bf16x8, t0); pf[1][s2] = __builtin_bit_cast(bf16x8, t1);
;         }
;     };
;     auto pv = [&](int vslot) {
;         const LAS unsigned char* vb_ = Vs + vslot * VS_BYTES + r * VS_STRIDE + 8 * hh;
; #pragma unroll
;         for (int kb = 0; kb < 2; ++kb)
; #pragma unroll
;             for (int s2 = 0; s2 < 2; ++s2)
; #pragma unroll
;                 for (int d = 0; d < 4; ++d) {
;                     const LAS unsigned char* p = vb_ + d * 32 * VS_STRIDE + (32 * kb + 16 * s2) * 2;
;                     const bf16x8 a = cat4(*(const LAS s16x4*)p, *(const LAS s16x4*)(p + 16));
;                     o[d] = MFMA32(a, pf[kb][s2], o[d]);
;                 }
;     };
.LBB0_40:
	v_add_u32_e32 v221, 0xc800, v216
	ds_read2_b64 v[222:225], v221 offset1:2
	v_add_u32_e32 v240, 0xf800, v216
	v_exp_f32_e32 v230, v86
	v_exp_f32_e32 v231, v87
	v_exp_f32_e32 v232, v88
	v_exp_f32_e32 v233, v89
	ds_read2_b64 v[86:89], v240 offset0:96 offset1:98
	v_exp_f32_e32 v234, v90
	v_exp_f32_e32 v235, v91
	v_add_u32_e32 v238, 0xd800, v216
	v_exp_f32_e32 v236, v92
	v_exp_f32_e32 v237, v93
	ds_read2_b64 v[90:93], v221 offset0:4 offset1:6
	v_exp_f32_e32 v80, v80
	v_exp_f32_e32 v81, v81
	v_exp_f32_e32 v82, v82
	v_exp_f32_e32 v83, v83
	v_exp_f32_e32 v84, v84
	v_exp_f32_e32 v85, v85
	v_cvt_pk_bf16_f32 v226, v80, v81
	v_cvt_pk_bf16_f32 v227, v82, v83
	v_cvt_pk_bf16_f32 v228, v84, v85
	v_cvt_pk_bf16_f32 v229, v230, v231
	v_add_u32_e32 v239, 0xe800, v216
	s_waitcnt lgkmcnt(0)
	v_mfma_f32_32x32x16_bf16 v[48:63], v[222:225], v[226:229], v[48:63]
	ds_read2_b64 v[222:225], v238 offset0:32 offset1:34
	v_mfma_f32_32x32x16_bf16 v[0:15], v[86:89], v[226:229], v[0:15]
	v_cvt_pk_bf16_f32 v88, v236, v237
	v_exp_f32_e32 v94, v94
	v_exp_f32_e32 v95, v95
	v_cvt_pk_bf16_f32 v86, v232, v233
	v_cvt_pk_bf16_f32 v87, v234, v235
	v_cvt_pk_bf16_f32 v89, v94, v95
	s_waitcnt lgkmcnt(0)
	v_mfma_f32_32x32x16_bf16 v[32:47], v[222:225], v[226:229], v[32:47]
	ds_read2_b64 v[222:225], v239 offset0:64 offset1:66
	v_mfma_f32_32x32x16_bf16 v[48:63], v[90:93], v[86:89], v[48:63]
	ds_read2_b64 v[90:93], v238 offset0:36 offset1:38
	s_waitcnt lgkmcnt(0)
	v_mfma_f32_32x32x16_bf16 v[32:47], v[90:93], v[86:89], v[32:47]
	ds_read2_b64 v[90:93], v239 offset0:68 offset1:70
	v_mfma_f32_32x32x16_bf16 v[16:31], v[222:225], v[226:229], v[16:31]
	v_exp_f32_e32 v226, v64
	v_exp_f32_e32 v227, v65
	ds_read2_b64 v[222:225], v240 offset0:100 offset1:102
	s_waitcnt lgkmcnt(0)
	v_mfma_f32_32x32x16_bf16 v[16:31], v[90:93], v[86:89], v[16:31]
	v_exp_f32_e32 v90, v66
	v_exp_f32_e32 v91, v67
	v_mov_b32_e32 v64, v68
	v_mov_b32_e32 v65, v69
	v_exp_f32_e32 v92, v64
	v_exp_f32_e32 v93, v65
	ds_read2_b64 v[64:67], v221 offset0:8 offset1:10
	v_mfma_f32_32x32x16_bf16 v[0:15], v[222:225], v[86:89], v[0:15]
	v_exp_f32_e32 v222, v70
	v_exp_f32_e32 v223, v71
	v_cvt_pk_bf16_f32 v68, v226, v227
	v_cvt_pk_bf16_f32 v69, v90, v91
	v_cvt_pk_bf16_f32 v70, v92, v93
	v_cvt_pk_bf16_f32 v71, v222, v223
	ds_read2_b64 v[86:89], v240 offset0:104 offset1:106
	s_waitcnt lgkmcnt(0)
	v_mfma_f32_32x32x16_bf16 v[48:63], v[64:67], v[68:71], v[48:63]
	ds_read2_b64 v[64:67], v238 offset0:40 offset1:42
	v_exp_f32_e32 v224, v72
	v_exp_f32_e32 v225, v73
	v_pk_add_f32 v[72:73], v[80:81], 0 op_sel_hi:[1,0]
	s_nop 0
	v_pk_add_f32 v[72:73], v[226:227], v[72:73]
	s_waitcnt lgkmcnt(0)
	v_mfma_f32_32x32x16_bf16 v[32:47], v[64:67], v[68:71], v[32:47]
	ds_read2_b64 v[64:67], v239 offset0:72 offset1:74
	v_add_f32_e64 v72, v82, v72
	v_add_f32_e64 v73, v83, v73
	v_add_f32_e64 v72, v90, v72
	v_add_f32_e64 v73, v91, v73
	v_pk_add_f32 v[80:81], v[84:85], v[72:73]
	s_waitcnt lgkmcnt(0)
	v_mfma_f32_32x32x16_bf16 v[16:31], v[64:67], v[68:71], v[16:31]
	v_mov_b32_e32 v64, v74
	v_mov_b32_e32 v65, v75
	ds_read2_b64 v[72:75], v239 offset0:76 offset1:78
	v_exp_f32_e32 v228, v64
	v_exp_f32_e32 v229, v65
	s_nop 0
	v_exp_f32_e32 v76, v76
	v_exp_f32_e32 v77, v77
	ds_read2_b64 v[64:67], v221 offset0:12 offset1:14
	v_mfma_f32_32x32x16_bf16 v[0:15], v[86:89], v[68:71], v[0:15]
	v_cvt_pk_bf16_f32 v70, v76, v77
	v_exp_f32_e32 v78, v78
	v_exp_f32_e32 v79, v79
	v_cvt_pk_bf16_f32 v68, v224, v225
	v_cvt_pk_bf16_f32 v69, v228, v229
	v_cvt_pk_bf16_f32 v71, v78, v79
	s_waitcnt lgkmcnt(0)
	s_nop 0
	v_mfma_f32_32x32x16_bf16 v[48:63], v[64:67], v[68:71], v[48:63]
	ds_read2_b64 v[64:67], v238 offset0:44 offset1:46
	s_waitcnt lgkmcnt(0)
	v_mfma_f32_32x32x16_bf16 v[32:47], v[64:67], v[68:71], v[32:47]
	v_add_f32_e64 v64, v92, v80
	v_add_f32_e64 v65, v93, v81
	v_add_f32_e64 v64, v230, v64
	v_add_f32_e64 v65, v231, v65
	v_add_f32_e64 v64, v222, v64
	v_add_f32_e64 v65, v223, v65
	v_pk_add_f32 v[64:65], v[232:233], v[64:65]
	v_mfma_f32_32x32x16_bf16 v[16:31], v[72:75], v[68:71], v[16:31]
	v_add_f32_e64 v64, v224, v64
	v_add_f32_e64 v65, v225, v65
	v_add_f32_e64 v80, v234, v64
	v_add_f32_e64 v81, v235, v65
	ds_read2_b64 v[64:67], v240 offset0:108 offset1:110
	v_pk_add_f32 v[72:73], v[228:229], v[80:81]
	s_nop 0
	v_pk_add_f32 v[72:73], v[236:237], v[72:73]
	s_waitcnt lgkmcnt(0)
	v_mfma_f32_32x32x16_bf16 v[0:15], v[64:67], v[68:71], v[0:15]
	v_add_f32_e64 v72, v76, v72
	v_add_f32_e64 v73, v77, v73
	v_add_f32_e64 v72, v94, v72
	v_add_f32_e64 v73, v95, v73
	v_add_f32_e64 v72, v78, v72
	v_add_f32_e64 v73, v79, v73
	v_add_f32_e32 v72, v72, v73
	v_add_f32_e32 v215, v215, v72
	s_branch .Lattn_wdone0
.LBB0_41:
	v_add_u32_e32 v64, 0x10c00, v252
	s_waitcnt vmcnt(0)
	ds_write_b128 v250, v[144:147] offset:25600
	ds_write_b128 v250, v[148:151] offset:38400
	ds_write_b128 v217, v[152:155] offset:25856
	ds_write2_b64 v64, v[156:157], v[158:159] offset1:1
	v_add_u32_e32 v64, 0x2200, v64
	ds_write2_b64 v64, v[160:161], v[162:163] offset1:1

; #define LAS __attribute__((address_space(3)))
; #define MFMA32(a, b, c) __builtin_amdgcn_mfma_f32_32x32x16_bf16((a), (b), (c), 0, 0, 0)
; DI void attn_unit(const Params& P, LAS unsigned char* lds, int b, int h, int qb, bool dry) {
;     ...
;     auto qk_softmax = [&](int kt, int kslot, bool domask) {
;         const LAS unsigned char* kb_ = Ks + kslot * KS_BYTES + r * KS_STRIDE + 16 * hh;
;         f32x16 s0, s1;
;         __builtin_amdgcn_s_setprio(1);
;         { const f32x16 z16 = {0.f, 0.f, 0.f, 0.f, 0.f, 0.f, 0.f, 0.f, 0.f, 0.f, 0.f, 0.f, 0.f, 0.f, 0.f, 0.f};
;           const bf16x8 a0 = *(const LAS bf16x8*)(kb_), a1 = *(const LAS bf16x8*)(kb_ + 32 * KS_STRIDE);
;           s0 = MFMA32(a0, qf[0], z16); s1 = MFMA32(a1, qf[0], z16); }
; #pragma unroll
;         for (int s = 1; s < 12; ++s) {
;             const bf16x8 a0 = *(const LAS bf16x8*)(kb_ + 32 * s), a1 = *(const LAS bf16x8*)(kb_ + 32 * KS_STRIDE + 32 * s);
;             s0 = MFMA32(a0, qf[s], s0); s1 = MFMA32(a1, qf[s], s1);
;         }
;         __builtin_amdgcn_s_setprio(0);
;         if (domask) {
;             const int qg = q0 + r, kbase = 64 * kt + 4 * hh;
; #pragma unroll
;             for (int i = 0; i < 16; ++i) { const int kk = kbase + (i & 3) + 8 * (i >> 2);
;                 if (kk > qg) s0[i] = -INFINITY;
;                 if (kk + 32 > qg) s1[i] = -INFINITY; }
;         }
.LBB0_45:
	s_add_i32 s42, s27, s20
	s_cmp_lg_u32 s42, 2
	s_setprio 1
	ds_read_b128 v[222:225], v220 offset:25600
	ds_read_b128 v[226:229], v220 offset:38400
	ds_read_b128 v[230:233], v220 offset:25632
	ds_read_b128 v[234:237], v220 offset:38432
	s_waitcnt lgkmcnt(3)
	v_mfma_f32_32x32x16_bf16 v[80:95], v[222:225], v[96:99], v[196:211]
	ds_read_b128 v[222:225], v220 offset:25664
	s_waitcnt lgkmcnt(3)
	v_mfma_f32_32x32x16_bf16 v[64:79], v[226:229], v[96:99], v[196:211]
	ds_read_b128 v[226:229], v220 offset:38464
	s_waitcnt lgkmcnt(3)
	v_mfma_f32_32x32x16_bf16 v[80:95], v[230:233], v[100:103], v[80:95]
	ds_read_b128 v[230:233], v220 offset:25696
	s_waitcnt lgkmcnt(3)
	v_mfma_f32_32x32x16_bf16 v[64:79], v[234:237], v[100:103], v[64:79]
	ds_read_b128 v[234:237], v220 offset:38496
	s_waitcnt lgkmcnt(3)
	v_mfma_f32_32x32x16_bf16 v[80:95], v[222:225], v[104:107], v[80:95]
	ds_read_b128 v[222:225], v220 offset:25728
	s_waitcnt lgkmcnt(3)
	v_mfma_f32_32x32x16_bf16 v[64:79], v[226:229], v[104:107], v[64:79]
	ds_read_b128 v[226:229], v220 offset:38528
	s_waitcnt lgkmcnt(3)
	v_mfma_f32_32x32x16_bf16 v[80:95], v[230:233], v[108:111], v[80:95]
	ds_read_b128 v[230:233], v220 offset:25760
	s_waitcnt lgkmcnt(3)
	v_mfma_f32_32x32x16_bf16 v[64:79], v[234:237], v[108:111], v[64:79]
	ds_read_b128 v[234:237], v220 offset:38560
	s_waitcnt lgkmcnt(3)
	v_mfma_f32_32x32x16_bf16 v[80:95], v[222:225], v[112:115], v[80:95]
	ds_read_b128 v[222:225], v220 offset:25792
	s_waitcnt lgkmcnt(3)
	v_mfma_f32_32x32x16_bf16 v[64:79], v[226:229], v[112:115], v[64:79]
	ds_read_b128 v[226:229], v220 offset:38592
	s_waitcnt lgkmcnt(3)
	v_mfma_f32_32x32x16_bf16 v[80:95], v[230:233], v[116:119], v[80:95]
	ds_read_b128 v[230:233], v220 offset:25824
	s_waitcnt lgkmcnt(3)
	v_mfma_f32_32x32x16_bf16 v[64:79], v[234:237], v[116:119], v[64:79]
	ds_read_b128 v[234:237], v220 offset:38624
	s_waitcnt lgkmcnt(3)
	v_mfma_f32_32x32x16_bf16 v[80:95], v[222:225], v[120:123], v[80:95]
	ds_read_b128 v[222:225], v220 offset:25856
	s_waitcnt lgkmcnt(3)
	v_mfma_f32_32x32x16_bf16 v[64:79], v[226:229], v[120:123], v[64:79]
	ds_read_b128 v[226:229], v220 offset:38656
	s_waitcnt lgkmcnt(3)
	v_mfma_f32_32x32x16_bf16 v[80:95], v[230:233], v[124:127], v[80:95]
	ds_read_b128 v[230:233], v220 offset:25888
	s_waitcnt lgkmcnt(3)
	v_mfma_f32_32x32x16_bf16 v[64:79], v[234:237], v[124:127], v[64:79]
	ds_read_b128 v[234:237], v220 offset:38688
	s_waitcnt lgkmcnt(3)
	v_mfma_f32_32x32x16_bf16 v[80:95], v[222:225], v[128:131], v[80:95]
	ds_read_b128 v[222:225], v220 offset:25920
	s_waitcnt lgkmcnt(3)
	v_mfma_f32_32x32x16_bf16 v[64:79], v[226:229], v[128:131], v[64:79]
	ds_read_b128 v[226:229], v220 offset:38720
	s_waitcnt lgkmcnt(3)
	v_mfma_f32_32x32x16_bf16 v[80:95], v[230:233], v[132:135], v[80:95]
	ds_read_b128 v[230:233], v220 offset:25952
	s_waitcnt lgkmcnt(3)
	v_mfma_f32_32x32x16_bf16 v[64:79], v[234:237], v[132:135], v[64:79]
	ds_read_b128 v[234:237], v220 offset:38752
	s_waitcnt lgkmcnt(3)
	v_mfma_f32_32x32x16_bf16 v[80:95], v[222:225], v[136:139], v[80:95]
	s_waitcnt lgkmcnt(2)
	v_mfma_f32_32x32x16_bf16 v[64:79], v[226:229], v[136:139], v[64:79]
	s_waitcnt lgkmcnt(1)
	v_mfma_f32_32x32x16_bf16 v[80:95], v[230:233], v[140:143], v[80:95]
	s_waitcnt lgkmcnt(0)
	v_mfma_f32_32x32x16_bf16 v[64:79], v[234:237], v[140:143], v[64:79]
	s_setprio 0
	s_nop 0
	s_mov_b64 vcc, s[40:41]
	s_cbranch_vccnz .Lattn_hw1_skip
	s_waitcnt vmcnt(5)
	ds_write_b128 v250, v[164:167]
	ds_write_b128 v250, v[168:171] offset:12800
	ds_write_b128 v251, v[172:175] offset:256
	ds_write2_b64 v253, v[176:177], v[178:179] offset1:1
	ds_write2_b64 v254, v[180:181], v[182:183] offset1:1
.Lattn_hw1_skip:
	s_cbranch_scc1 .LBB0_47
	v_add_u32_e32 v221, 0x60, v219
	v_add_u32_e32 v220, 64, v219
	v_cmp_le_i32_e32 vcc, v221, v214
	s_nop 6
	v_cndmask_b32_e32 v64, v249, v64, vcc
	v_cmp_lt_i32_e32 vcc, v220, v214
	s_nop 1
	v_cndmask_b32_e32 v81, v249, v81, vcc
	v_cmp_le_i32_e32 vcc, v220, v214
	v_add_u32_e32 v220, 0x61, v219
	s_nop 0
	v_cndmask_b32_e32 v80, v249, v80, vcc
	v_cmp_le_i32_e32 vcc, v220, v214
	v_add_u32_e32 v220, 0x42, v219
	s_nop 0
	v_cndmask_b32_e32 v65, v249, v65, vcc
	v_cmp_le_i32_e32 vcc, v220, v214
	v_add_u32_e32 v220, 0x62, v219
	s_nop 0
	v_cndmask_b32_e32 v82, v249, v82, vcc
	v_cmp_le_i32_e32 vcc, v220, v214
	v_add_u32_e32 v220, 0x43, v219
	s_nop 0
	v_cndmask_b32_e32 v66, v249, v66, vcc
	v_cmp_le_i32_e32 vcc, v220, v214
	v_add_u32_e32 v220, 0x63, v219
	s_nop 0
	v_cndmask_b32_e32 v83, v249, v83, vcc
	v_cmp_le_i32_e32 vcc, v220, v214
	v_add_u32_e32 v220, 0x48, v219
	s_nop 0
	v_cndmask_b32_e32 v67, v249, v67, vcc
	v_cmp_le_i32_e32 vcc, v220, v214
	v_add_u32_e32 v220, 0x68, v219
	s_nop 0
	v_cndmask_b32_e32 v84, v249, v84, vcc
	v_cmp_le_i32_e32 vcc, v220, v214
	v_add_u32_e32 v220, 0x49, v219
	s_nop 0
	v_cndmask_b32_e32 v68, v249, v68, vcc
	v_cmp_le_i32_e32 vcc, v220, v214
	v_add_u32_e32 v220, 0x69, v219
	s_nop 0
	v_cndmask_b32_e32 v85, v249, v85, vcc
	v_cmp_le_i32_e32 vcc, v220, v214
	v_add_u32_e32 v220, 0x4a, v219
	s_nop 0
	v_cndmask_b32_e32 v69, v249, v69, vcc
	v_cmp_le_i32_e32 vcc, v220, v214
	v_add_u32_e32 v220, 0x6a, v219
	s_nop 0
	v_cndmask_b32_e32 v86, v249, v86, vcc
	v_cmp_le_i32_e32 vcc, v220, v214
	v_add_u32_e32 v220, 0x4b, v219
	s_nop 0
	v_cndmask_b32_e32 v70, v249, v70, vcc
	v_cmp_le_i32_e32 vcc, v220, v214
	v_add_u32_e32 v220, 0x6b, v219
	s_nop 0
	v_cndmask_b32_e32 v87, v249, v87, vcc
	v_cmp_le_i32_e32 vcc, v220, v214
	v_add_u32_e32 v220, 0x50, v219
	s_nop 0
	v_cndmask_b32_e32 v71, v249, v71, vcc
	v_cmp_le_i32_e32 vcc, v220, v214
	v_add_u32_e32 v220, 0x70, v219
	s_nop 0
	v_cndmask_b32_e32 v88, v249, v88, vcc
	v_cmp_le_i32_e32 vcc, v220, v214
; DI void attn_unit(const Params& P, LAS unsigned char* lds, int b, int h, int qb, bool dry) {
;     ...
;         if (domask) {
;             const int qg = q0 + r, kbase = 64 * kt + 4 * hh;
; #pragma unroll
;             for (int i = 0; i < 16; ++i) { const int kk = kbase + (i & 3) + 8 * (i >> 2);
;                 if (kk > qg) s0[i] = -INFINITY;
;                 if (kk + 32 > qg) s1[i] = -INFINITY; }
;         }
;         float mx = fmaxf(fmaxf(s0[0], s0[1]), s0[2]);
; #pragma unroll
;         for (int i = 3; i < 15; i += 2) mx = fmaxf(fmaxf(mx, s0[i]), s0[i + 1]);
;         mx = fmaxf(fmaxf(mx, s0[15]), s1[0]);
; #pragma unroll
;         for (int i = 1; i < 15; i += 2) mx = fmaxf(fmaxf(mx, s1[i]), s1[i + 1]);
;         mx = fmaxf(mx, s1[15]);
;         { const auto rr = __builtin_amdgcn_permlane32_swap(__float_as_uint(mx), __float_as_uint(mx), false, false);
;           mx = fmaxf(__uint_as_float(rr[0]), __uint_as_float(rr[1])); }
;         if (__builtin_amdgcn_ballot_w64(mx > mrun + 8.f)) {
;             const float mnew = fmaxf(mrun, mx);
;             const float alpha = __builtin_amdgcn_exp2f(mrun - mnew);
;             mrun = mnew; lrun *= alpha;
; #pragma unroll
;             for (int d = 0; d < 4; ++d) o[d] = o[d] * alpha;
;         }
	v_add_u32_e32 v220, 0x51, v219
	s_nop 0
	v_cndmask_b32_e32 v72, v249, v72, vcc
	v_cmp_le_i32_e32 vcc, v220, v214
	v_add_u32_e32 v220, 0x71, v219
	s_nop 0
	v_cndmask_b32_e32 v89, v249, v89, vcc
	v_cmp_le_i32_e32 vcc, v220, v214
	v_add_u32_e32 v220, 0x52, v219
	s_nop 0
	v_cndmask_b32_e32 v73, v249, v73, vcc
	v_cmp_le_i32_e32 vcc, v220, v214
	v_add_u32_e32 v220, 0x72, v219
	s_nop 0
	v_cndmask_b32_e32 v90, v249, v90, vcc
	v_cmp_le_i32_e32 vcc, v220, v214
	v_add_u32_e32 v220, 0x53, v219
	s_nop 0
	v_cndmask_b32_e32 v74, v249, v74, vcc
	v_cmp_le_i32_e32 vcc, v220, v214
	v_add_u32_e32 v220, 0x73, v219
	s_nop 0
	v_cndmask_b32_e32 v91, v249, v91, vcc
	v_cmp_le_i32_e32 vcc, v220, v214
	v_add_u32_e32 v220, 0x58, v219
	s_nop 0
	v_cndmask_b32_e32 v75, v249, v75, vcc
	v_cmp_le_i32_e32 vcc, v220, v214
	v_add_u32_e32 v220, 0x78, v219
	s_nop 0
	v_cndmask_b32_e32 v92, v249, v92, vcc
	v_cmp_le_i32_e32 vcc, v220, v214
	v_add_u32_e32 v220, 0x59, v219
	s_nop 0
	v_cndmask_b32_e32 v76, v249, v76, vcc
	v_cmp_le_i32_e32 vcc, v220, v214
	v_add_u32_e32 v220, 0x79, v219
	s_nop 0
	v_cndmask_b32_e32 v93, v249, v93, vcc
	v_cmp_le_i32_e32 vcc, v220, v214
	v_add_u32_e32 v220, 0x5a, v219
	s_nop 0
	v_cndmask_b32_e32 v77, v249, v77, vcc
	v_cmp_le_i32_e32 vcc, v220, v214
	v_add_u32_e32 v220, 0x7a, v219
	s_nop 0
	v_cndmask_b32_e32 v94, v249, v94, vcc
	v_cmp_le_i32_e32 vcc, v220, v214
	v_add_u32_e32 v220, 0x5b, v219
	s_nop 0
	v_cndmask_b32_e32 v78, v249, v78, vcc
	v_cmp_le_i32_e32 vcc, v220, v214
	v_add_u32_e32 v220, 0x7b, v219
	s_nop 0
	v_cndmask_b32_e32 v95, v249, v95, vcc
	v_cmp_le_i32_e32 vcc, v220, v214
	s_nop 1
	v_cndmask_b32_e32 v79, v249, v79, vcc
.LBB0_47:
	s_nop 6
	v_max_f32_e32 v220, v81, v81
	v_max_f32_e32 v221, v80, v80
	v_max_f32_e32 v220, v221, v220
	v_max3_f32 v220, v220, v82, v83
	v_max3_f32 v220, v220, v84, v85
	v_max3_f32 v220, v220, v86, v87
	v_max3_f32 v220, v220, v88, v89
	v_max3_f32 v220, v220, v90, v91
	v_max3_f32 v220, v220, v92, v93
	v_max3_f32 v220, v220, v94, v95
	v_max3_f32 v220, v220, v64, v65
	v_max3_f32 v220, v220, v66, v67
	v_max3_f32 v220, v220, v68, v69
	v_max3_f32 v220, v220, v70, v71
	v_max3_f32 v220, v220, v72, v73
	v_max3_f32 v220, v220, v74, v75
	v_max3_f32 v220, v220, v76, v77
	v_max3_f32 v220, v220, v78, v79
	v_mov_b32_e32 v221, v220
	s_nop 1
	v_permlane32_swap_b32_e32 v220, v221
	v_max_f32_e32 v221, v221, v221
	v_max_f32_e32 v220, v220, v220
	v_max_f32_e32 v220, v220, v221
	v_cmp_lt_f32_e32 vcc, 0x41000000, v220
	s_cbranch_vccz .LBB0_49
.Lfold_r1:
	v_max_f32_e32 v221, 0, v220
	v_sub_f32_e32 v194, 0, v221
	v_exp_f32_e32 v194, v194
	s_nop 0
	v_mul_f32_e32 v215, v215, v194
	v_pk_mul_f32 v[62:63], v[62:63], v[194:195] op_sel_hi:[1,0]
	v_pk_mul_f32 v[60:61], v[60:61], v[194:195] op_sel_hi:[1,0]
	v_pk_mul_f32 v[58:59], v[58:59], v[194:195] op_sel_hi:[1,0]
	v_pk_mul_f32 v[56:57], v[56:57], v[194:195] op_sel_hi:[1,0]
	v_pk_mul_f32 v[54:55], v[54:55], v[194:195] op_sel_hi:[1,0]
	v_pk_mul_f32 v[52:53], v[52:53], v[194:195] op_sel_hi:[1,0]
	v_pk_mul_f32 v[50:51], v[50:51], v[194:195] op_sel_hi:[1,0]
	v_pk_mul_f32 v[48:49], v[48:49], v[194:195] op_sel_hi:[1,0]
	v_pk_mul_f32 v[46:47], v[46:47], v[194:195] op_sel_hi:[1,0]
	v_pk_mul_f32 v[44:45], v[44:45], v[194:195] op_sel_hi:[1,0]
	v_pk_mul_f32 v[42:43], v[42:43], v[194:195] op_sel_hi:[1,0]
	v_pk_mul_f32 v[40:41], v[40:41], v[194:195] op_sel_hi:[1,0]
	v_pk_mul_f32 v[38:39], v[38:39], v[194:195] op_sel_hi:[1,0]
	v_pk_mul_f32 v[36:37], v[36:37], v[194:195] op_sel_hi:[1,0]
	v_pk_mul_f32 v[34:35], v[34:35], v[194:195] op_sel_hi:[1,0]
	v_pk_mul_f32 v[32:33], v[32:33], v[194:195] op_sel_hi:[1,0]
	v_pk_mul_f32 v[30:31], v[30:31], v[194:195] op_sel_hi:[1,0]
	v_pk_mul_f32 v[28:29], v[28:29], v[194:195] op_sel_hi:[1,0]
	v_pk_mul_f32 v[26:27], v[26:27], v[194:195] op_sel_hi:[1,0]
	v_pk_mul_f32 v[24:25], v[24:25], v[194:195] op_sel_hi:[1,0]
	v_pk_mul_f32 v[22:23], v[22:23], v[194:195] op_sel_hi:[1,0]
	v_pk_mul_f32 v[20:21], v[20:21], v[194:195] op_sel_hi:[1,0]
	v_pk_mul_f32 v[18:19], v[18:19], v[194:195] op_sel_hi:[1,0]
	v_pk_mul_f32 v[16:17], v[16:17], v[194:195] op_sel_hi:[1,0]
	v_pk_mul_f32 v[14:15], v[14:15], v[194:195] op_sel_hi:[1,0]
	v_pk_mul_f32 v[12:13], v[12:13], v[194:195] op_sel_hi:[1,0]
	v_pk_mul_f32 v[10:11], v[10:11], v[194:195] op_sel_hi:[1,0]
	v_pk_mul_f32 v[8:9], v[8:9], v[194:195] op_sel_hi:[1,0]
	v_pk_mul_f32 v[6:7], v[6:7], v[194:195] op_sel_hi:[1,0]
	v_pk_mul_f32 v[4:5], v[4:5], v[194:195] op_sel_hi:[1,0]
	v_pk_mul_f32 v[2:3], v[2:3], v[194:195] op_sel_hi:[1,0]
	v_pk_mul_f32 v[0:1], v[0:1], v[194:195] op_sel_hi:[1,0]
	v_sub_f32_e32 v196, v196, v221
	v_sub_f32_e32 v197, v197, v221
	v_sub_f32_e32 v198, v198, v221
	v_sub_f32_e32 v199, v199, v221
	v_sub_f32_e32 v200, v200, v221
	v_sub_f32_e32 v201, v201, v221
	v_sub_f32_e32 v202, v202, v221
	v_sub_f32_e32 v203, v203, v221
	v_sub_f32_e32 v204, v204, v221
	v_sub_f32_e32 v205, v205, v221
	v_sub_f32_e32 v206, v206, v221
	v_sub_f32_e32 v207, v207, v221
	v_sub_f32_e32 v208, v208, v221
	v_sub_f32_e32 v209, v209, v221
	v_sub_f32_e32 v210, v210, v221
	v_sub_f32_e32 v211, v211, v221
	v_sub_f32_e32 v64, v64, v221
	v_sub_f32_e32 v65, v65, v221
	v_sub_f32_e32 v66, v66, v221
	v_sub_f32_e32 v67, v67, v221
	v_sub_f32_e32 v68, v68, v221
	v_sub_f32_e32 v69, v69, v221
	v_sub_f32_e32 v70, v70, v221
	v_sub_f32_e32 v71, v71, v221
	v_sub_f32_e32 v72, v72, v221
	v_sub_f32_e32 v73, v73, v221
	v_sub_f32_e32 v74, v74, v221
	v_sub_f32_e32 v75, v75, v221
	v_sub_f32_e32 v76, v76, v221
	v_sub_f32_e32 v77, v77, v221
	v_sub_f32_e32 v78, v78, v221
	v_sub_f32_e32 v79, v79, v221
	v_sub_f32_e32 v80, v80, v221
	v_sub_f32_e32 v81, v81, v221
	v_sub_f32_e32 v82, v82, v221
	v_sub_f32_e32 v83, v83, v221
	v_sub_f32_e32 v84, v84, v221
	v_sub_f32_e32 v85, v85, v221
	v_sub_f32_e32 v86, v86, v221
	v_sub_f32_e32 v87, v87, v221
	v_sub_f32_e32 v88, v88, v221
	v_sub_f32_e32 v89, v89, v221
	v_sub_f32_e32 v90, v90, v221
	v_sub_f32_e32 v91, v91, v221
	v_sub_f32_e32 v92, v92, v221
	v_sub_f32_e32 v93, v93, v221
	v_sub_f32_e32 v94, v94, v221
	v_sub_f32_e32 v95, v95, v221
; #define LAS __attribute__((address_space(3)))
; DI unsigned pk_bf16(float lo, float hi) { unsigned r; asm("v_cvt_pk_bf16_f32 %0, %1, %2" : "=v"(r) : "v"(lo), "v"(hi)); return r; }
; #define MFMA32(a, b, c) __builtin_amdgcn_mfma_f32_32x32x16_bf16((a), (b), (c), 0, 0, 0)
; DI bf16x8 cat4(s16x4 lo, s16x4 hi) { return __builtin_shufflevector(lo, hi, 0, 1, 2, 3, 4, 5, 6, 7); }
; DI void attn_unit(const Params& P, LAS unsigned char* lds, int b, int h, int qb, bool dry) {
;     ...
;         f32x2_ ls2 = {0.f, 0.f};
;         const f32x2_ m2 = {mrun, mrun};
; #pragma unroll
;         for (int i = 0; i < 16; i += 2) {
;             f32x2_ t = (f32x2_){s0[i], s0[i + 1]} - m2; t.x = __builtin_amdgcn_exp2f(t.x); t.y = __builtin_amdgcn_exp2f(t.y); ls2 += t; s0[i] = t.x; s0[i + 1] = t.y;
;             f32x2_ u = (f32x2_){s1[i], s1[i + 1]} - m2; u.x = __builtin_amdgcn_exp2f(u.x); u.y = __builtin_amdgcn_exp2f(u.y); ls2 += u; s1[i] = u.x; s1[i + 1] = u.y;
;         }
;         lrun += ls2.x + ls2.y;
; #pragma unroll
;         for (int s2 = 0; s2 < 2; ++s2) {
;             u32x4 t0, t1;
;             t0.x = pk_bf16(s0[8 * s2 + 0], s0[8 * s2 + 1]); t0.y = pk_bf16(s0[8 * s2 + 2], s0[8 * s2 + 3]); t0.z = pk_bf16(s0[8 * s2 + 4], s0[8 * s2 + 5]); t0.w = pk_bf16(s0[8 * s2 + 6], s0[8 * s2 + 7]);
;             t1.x = pk_bf16(s1[8 * s2 + 0], s1[8 * s2 + 1]); t1.y = pk_bf16(s1[8 * s2 + 2], s1[8 * s2 + 3]); t1.z = pk_bf16(s1[8 * s2 + 4], s1[8 * s2 + 5]); t1.w = pk_bf16(s1[8 * s2 + 6], s1[8 * s2 + 7]);
;             pf[0][s2] = __builtin_bit_cast(bf16x8, t0); pf[1][s2] = __builtin_bit_cast(bf16x8, t1);
;         }
;     };
;     auto pv = [&](int vslot) {
;         const LAS unsigned char* vb_ = Vs + vslot * VS_BYTES + r * VS_STRIDE + 8 * hh;
; #pragma unroll
;         for (int kb = 0; kb < 2; ++kb)
; #pragma unroll
;             for (int s2 = 0; s2 < 2; ++s2)
; #pragma unroll
;                 for (int d = 0; d < 4; ++d) {
;                     const LAS unsigned char* p = vb_ + d * 32 * VS_STRIDE + (32 * kb + 16 * s2) * 2;
;                     const bf16x8 a = cat4(*(const LAS s16x4*)p, *(const LAS s16x4*)(p + 16));
;                     o[d] = MFMA32(a, pf[kb][s2], o[d]);
;                 }
.LBB0_49:
	ds_read2_b64 v[220:223], v218 offset1:2
	v_add_u32_e32 v238, 0x3000, v218
	v_exp_f32_e32 v228, v86
	v_exp_f32_e32 v229, v87
	v_exp_f32_e32 v230, v88
	v_exp_f32_e32 v231, v89
	ds_read2_b64 v[86:89], v238 offset0:96 offset1:98
	v_exp_f32_e32 v232, v90
	v_exp_f32_e32 v233, v91
	v_add_u32_e32 v236, 0x1000, v218
	v_exp_f32_e32 v234, v92
	v_exp_f32_e32 v235, v93
	ds_read2_b64 v[90:93], v218 offset0:4 offset1:6
	v_exp_f32_e32 v80, v80
	v_exp_f32_e32 v81, v81
	v_exp_f32_e32 v82, v82
	v_exp_f32_e32 v83, v83
	v_exp_f32_e32 v84, v84
	v_exp_f32_e32 v85, v85
	v_cvt_pk_bf16_f32 v224, v80, v81
	v_cvt_pk_bf16_f32 v225, v82, v83
	v_cvt_pk_bf16_f32 v226, v84, v85
	v_cvt_pk_bf16_f32 v227, v228, v229
	v_add_u32_e32 v237, 0x2000, v218
	s_waitcnt lgkmcnt(0)
	v_mfma_f32_32x32x16_bf16 v[48:63], v[220:223], v[224:227], v[48:63]
	ds_read2_b64 v[220:223], v236 offset0:32 offset1:34
	v_mfma_f32_32x32x16_bf16 v[0:15], v[86:89], v[224:227], v[0:15]
	v_cvt_pk_bf16_f32 v88, v234, v235
	v_exp_f32_e32 v94, v94
	v_exp_f32_e32 v95, v95
	v_cvt_pk_bf16_f32 v86, v230, v231
	v_cvt_pk_bf16_f32 v87, v232, v233
	v_cvt_pk_bf16_f32 v89, v94, v95
	s_waitcnt lgkmcnt(0)
	v_mfma_f32_32x32x16_bf16 v[32:47], v[220:223], v[224:227], v[32:47]
	ds_read2_b64 v[220:223], v237 offset0:64 offset1:66
	v_mfma_f32_32x32x16_bf16 v[48:63], v[90:93], v[86:89], v[48:63]
	ds_read2_b64 v[90:93], v236 offset0:36 offset1:38
	s_waitcnt lgkmcnt(0)
	v_mfma_f32_32x32x16_bf16 v[32:47], v[90:93], v[86:89], v[32:47]
	ds_read2_b64 v[90:93], v237 offset0:68 offset1:70
	v_mfma_f32_32x32x16_bf16 v[16:31], v[220:223], v[224:227], v[16:31]
	v_exp_f32_e32 v224, v64
	v_exp_f32_e32 v225, v65
	ds_read2_b64 v[220:223], v238 offset0:100 offset1:102
	s_waitcnt lgkmcnt(0)
	v_mfma_f32_32x32x16_bf16 v[16:31], v[90:93], v[86:89], v[16:31]
	v_exp_f32_e32 v90, v66
	v_exp_f32_e32 v91, v67
	v_mov_b32_e32 v64, v68
	v_mov_b32_e32 v65, v69
	v_exp_f32_e32 v92, v64
	v_exp_f32_e32 v93, v65
	ds_read2_b64 v[64:67], v218 offset0:8 offset1:10
	v_mfma_f32_32x32x16_bf16 v[0:15], v[220:223], v[86:89], v[0:15]
	v_exp_f32_e32 v220, v70
	v_exp_f32_e32 v221, v71
	v_cvt_pk_bf16_f32 v68, v224, v225
	v_cvt_pk_bf16_f32 v69, v90, v91
	v_cvt_pk_bf16_f32 v70, v92, v93
	v_cvt_pk_bf16_f32 v71, v220, v221
	ds_read2_b64 v[86:89], v238 offset0:104 offset1:106
	s_waitcnt lgkmcnt(0)
	v_mfma_f32_32x32x16_bf16 v[48:63], v[64:67], v[68:71], v[48:63]
	ds_read2_b64 v[64:67], v236 offset0:40 offset1:42
	v_exp_f32_e32 v222, v72
	v_exp_f32_e32 v223, v73
	v_pk_add_f32 v[72:73], v[80:81], 0 op_sel_hi:[1,0]
	s_nop 0
	v_pk_add_f32 v[72:73], v[224:225], v[72:73]
	s_waitcnt lgkmcnt(0)
	v_mfma_f32_32x32x16_bf16 v[32:47], v[64:67], v[68:71], v[32:47]
	ds_read2_b64 v[64:67], v237 offset0:72 offset1:74
	v_add_f32_e64 v72, v82, v72
	v_add_f32_e64 v73, v83, v73
	v_add_f32_e64 v72, v90, v72
	v_add_f32_e64 v73, v91, v73
	v_pk_add_f32 v[80:81], v[84:85], v[72:73]
	s_waitcnt lgkmcnt(0)
	v_mfma_f32_32x32x16_bf16 v[16:31], v[64:67], v[68:71], v[16:31]
	v_mov_b32_e32 v64, v74
	v_mov_b32_e32 v65, v75
	ds_read2_b64 v[72:75], v237 offset0:76 offset1:78
	v_exp_f32_e32 v226, v64
	v_exp_f32_e32 v227, v65
	s_nop 0
	v_exp_f32_e32 v76, v76
	v_exp_f32_e32 v77, v77
	ds_read2_b64 v[64:67], v218 offset0:12 offset1:14
	v_mfma_f32_32x32x16_bf16 v[0:15], v[86:89], v[68:71], v[0:15]
	v_cvt_pk_bf16_f32 v70, v76, v77
	v_exp_f32_e32 v78, v78
	v_exp_f32_e32 v79, v79
	v_cvt_pk_bf16_f32 v68, v222, v223
	v_cvt_pk_bf16_f32 v69, v226, v227
	v_cvt_pk_bf16_f32 v71, v78, v79
	s_waitcnt lgkmcnt(0)
	s_nop 0
	v_mfma_f32_32x32x16_bf16 v[48:63], v[64:67], v[68:71], v[48:63]
	ds_read2_b64 v[64:67], v236 offset0:44 offset1:46
	s_waitcnt lgkmcnt(0)
	v_mfma_f32_32x32x16_bf16 v[32:47], v[64:67], v[68:71], v[32:47]
	v_add_f32_e64 v64, v92, v80
	v_add_f32_e64 v65, v93, v81
	v_add_f32_e64 v64, v228, v64
	v_add_f32_e64 v65, v229, v65
	v_add_f32_e64 v64, v220, v64
	v_add_f32_e64 v65, v221, v65
	v_pk_add_f32 v[64:65], v[230:231], v[64:65]
	v_mfma_f32_32x32x16_bf16 v[16:31], v[72:75], v[68:71], v[16:31]
	v_add_f32_e64 v64, v222, v64
	v_add_f32_e64 v65, v223, v65
	v_add_f32_e64 v80, v232, v64
	v_add_f32_e64 v81, v233, v65
	ds_read2_b64 v[64:67], v238 offset0:108 offset1:110
	v_pk_add_f32 v[72:73], v[226:227], v[80:81]
	s_nop 0
	v_pk_add_f32 v[72:73], v[234:235], v[72:73]
	s_waitcnt lgkmcnt(0)
	v_mfma_f32_32x32x16_bf16 v[0:15], v[64:67], v[68:71], v[0:15]
	v_add_f32_e64 v72, v76, v72
	v_add_f32_e64 v73, v77, v73
	v_add_f32_e64 v72, v94, v72
	v_add_f32_e64 v73, v95, v73
	v_add_f32_e64 v72, v78, v72
	v_add_f32_e64 v73, v79, v73
	v_add_f32_e32 v72, v72, v73
	v_add_f32_e32 v215, v215, v72
	s_branch .LBB0_32
.LBB0_50:
	s_waitcnt vmcnt(5)
	ds_write_b128 v250, v[164:167]
	ds_write_b128 v250, v[168:171] offset:12800
	ds_write_b128 v251, v[172:175] offset:256
	ds_write2_b64 v253, v[176:177], v[178:179] offset1:1
	ds_write2_b64 v254, v[180:181], v[182:183] offset1:1
	s_branch .LBB0_32
; DI unsigned pk_bf16(float lo, float hi) { unsigned r; asm("v_cvt_pk_bf16_f32 %0, %1, %2" : "=v"(r) : "v"(lo), "v"(hi)); return r; }
; DI void attn_unit(const Params& P, LAS unsigned char* lds, int b, int h, int qb, bool dry) {
;     ...
;     float lt; { const auto rr = __builtin_amdgcn_permlane32_swap(__float_as_uint(lrun), __float_as_uint(lrun), false, false); lt = __uint_as_float(rr[0]) + __uint_as_float(rr[1]); }
;     const float inv = 1.f / lt;
;     if (dry) { float tt = 0.f;
; #pragma unroll
;         for (int d = 0; d < 4; ++d)
; #pragma unroll
;             for (int i = 0; i < 16; ++i) tt += o[d][i];
;         if (tt * inv != 123456.789f) return; }
; #pragma unroll
;     for (int d = 0; d < 4; ++d)
; #pragma unroll
;         for (int g = 0; g < 4; ++g) {
;             u32x2 ov; ov.x = pk_bf16(o[d][4 * g] * inv, o[d][4 * g + 1] * inv); ov.y = pk_bf16(o[d][4 * g + 2] * inv, o[d][4 * g + 3] * inv);
;             *(u32x2*)(qrow + 32 * d + 8 * g + 4 * hh) = ov;
;         }
.LBB0_51:
	v_mov_b32_e32 v64, v215
	s_nop 1
	v_permlane32_swap_b32_e32 v215, v64
	v_add_f32_e32 v64, v215, v64
	v_div_scale_f32 v65, s[26:27], v64, v64, 1.0
	v_rcp_f32_e32 v66, v65
	v_lshlrev_b32_e32 v184, 1, v212
	s_and_b32 s20, s56, 31
	s_lshl_b32 s53, s20, 2
	v_fma_f32 v67, -v65, v66, 1.0
	v_fmac_f32_e32 v66, v67, v66
	v_div_scale_f32 v67, vcc, 1.0, v64, 1.0
	v_mul_f32_e32 v68, v67, v66
	v_fma_f32 v69, -v65, v68, v67
	v_fmac_f32_e32 v68, v69, v66
	v_fma_f32 v65, -v65, v68, v67
	v_div_fmas_f32 v65, v65, v66, v68
	v_div_fixup_f32 v66, v65, v64, 1.0
	v_mul_f32_e32 v32, v32, v66
	v_mul_f32_e32 v33, v33, v66
	v_mul_f32_e32 v48, v48, v66
	v_mul_f32_e32 v49, v49, v66
	v_cvt_pk_bf16_f32 v32, v32, v33
	v_mul_f32_e32 v33, v34, v66
	v_mul_f32_e32 v16, v16, v66
	v_mul_f32_e32 v17, v17, v66
	v_mul_f32_e32 v0, v0, v66
	v_mul_f32_e32 v1, v1, v66
	v_lshl_add_u64 v[64:65], v[186:187], 0, v[184:185]
	v_cvt_pk_bf16_f32 v48, v48, v49
	v_mul_f32_e32 v49, v50, v66
	v_mul_f32_e32 v34, v35, v66
	v_cvt_pk_bf16_f32 v33, v33, v34
	v_cvt_pk_bf16_f32 v16, v16, v17
	v_mul_f32_e32 v17, v18, v66
	v_cvt_pk_bf16_f32 v0, v0, v1
	v_mul_f32_e32 v1, v2, v66
	v_mul_f32_e32 v50, v51, v66
	v_cvt_pk_bf16_f32 v49, v49, v50
	global_store_dwordx2 v[64:65], v[32:33], off offset:64
	v_mul_f32_e32 v32, v36, v66
	v_mul_f32_e32 v33, v37, v66
	v_mul_f32_e32 v18, v19, v66
	v_cvt_pk_bf16_f32 v17, v17, v18
	v_mul_f32_e32 v2, v3, v66
	v_cvt_pk_bf16_f32 v1, v1, v2
	global_store_dwordx2 v[64:65], v[48:49], off
	v_mul_f32_e32 v48, v52, v66
	v_mul_f32_e32 v49, v53, v66
	v_cvt_pk_bf16_f32 v32, v32, v33
	v_mul_f32_e32 v33, v38, v66
	global_store_dwordx2 v[64:65], v[16:17], off offset:128
	v_mul_f32_e32 v16, v20, v66
	v_mul_f32_e32 v17, v21, v66
	global_store_dwordx2 v[64:65], v[0:1], off offset:192
	v_mul_f32_e32 v0, v4, v66
	v_mul_f32_e32 v1, v5, v66
	v_cvt_pk_bf16_f32 v48, v48, v49
	v_mul_f32_e32 v49, v54, v66
	v_mul_f32_e32 v34, v39, v66
	v_cvt_pk_bf16_f32 v33, v33, v34
	v_cvt_pk_bf16_f32 v16, v16, v17
	v_mul_f32_e32 v17, v22, v66
	v_cvt_pk_bf16_f32 v0, v0, v1
	v_mul_f32_e32 v1, v6, v66
	v_mul_f32_e32 v50, v55, v66
	v_cvt_pk_bf16_f32 v49, v49, v50
	global_store_dwordx2 v[64:65], v[32:33], off offset:80
	v_mul_f32_e32 v32, v40, v66
	v_mul_f32_e32 v33, v41, v66
	v_mul_f32_e32 v18, v23, v66
	v_cvt_pk_bf16_f32 v17, v17, v18
	v_mul_f32_e32 v2, v7, v66
	v_cvt_pk_bf16_f32 v1, v1, v2
	global_store_dwordx2 v[64:65], v[48:49], off offset:16
	v_mul_f32_e32 v48, v56, v66
	v_mul_f32_e32 v49, v57, v66
	v_cvt_pk_bf16_f32 v32, v32, v33
	v_mul_f32_e32 v33, v42, v66
	global_store_dwordx2 v[64:65], v[16:17], off offset:144
	v_mul_f32_e32 v16, v24, v66
	v_mul_f32_e32 v17, v25, v66
	global_store_dwordx2 v[64:65], v[0:1], off offset:208
	v_mul_f32_e32 v0, v8, v66
	v_mul_f32_e32 v1, v9, v66
	v_cvt_pk_bf16_f32 v48, v48, v49
	v_mul_f32_e32 v49, v58, v66
	v_mul_f32_e32 v34, v43, v66
	v_cvt_pk_bf16_f32 v33, v33, v34
	v_cvt_pk_bf16_f32 v16, v16, v17
	v_mul_f32_e32 v17, v26, v66
	v_cvt_pk_bf16_f32 v0, v0, v1
	v_mul_f32_e32 v1, v10, v66
	v_mul_f32_e32 v50, v59, v66
	v_cvt_pk_bf16_f32 v49, v49, v50
	global_store_dwordx2 v[64:65], v[32:33], off offset:96
	v_mul_f32_e32 v32, v44, v66
	v_mul_f32_e32 v33, v45, v66
	v_mul_f32_e32 v18, v27, v66
	v_cvt_pk_bf16_f32 v17, v17, v18
	v_mul_f32_e32 v2, v11, v66
	v_cvt_pk_bf16_f32 v1, v1, v2
	global_store_dwordx2 v[64:65], v[48:49], off offset:32
	v_mul_f32_e32 v48, v60, v66
	v_mul_f32_e32 v49, v61, v66
	v_cvt_pk_bf16_f32 v32, v32, v33
	v_mul_f32_e32 v33, v46, v66
	global_store_dwordx2 v[64:65], v[16:17], off offset:160
	v_mul_f32_e32 v16, v28, v66
	v_mul_f32_e32 v17, v29, v66
	global_store_dwordx2 v[64:65], v[0:1], off offset:224
	v_mul_f32_e32 v0, v12, v66
	v_mul_f32_e32 v1, v13, v66
	v_cvt_pk_bf16_f32 v48, v48, v49
	v_mul_f32_e32 v49, v62, v66
	v_mul_f32_e32 v34, v47, v66
	v_cvt_pk_bf16_f32 v33, v33, v34
	global_store_dwordx2 v[64:65], v[32:33], off offset:112
	v_cvt_pk_bf16_f32 v16, v16, v17
	v_mul_f32_e32 v17, v30, v66
	v_cvt_pk_bf16_f32 v0, v0, v1
	v_mul_f32_e32 v1, v14, v66
	v_mov_b32_e32 v32, v195
	v_mul_f32_e32 v50, v63, v66
	v_cvt_pk_bf16_f32 v49, v49, v50
	global_store_dwordx2 v[64:65], v[48:49], off offset:48
	v_mul_f32_e32 v18, v31, v66
	v_cvt_pk_bf16_f32 v17, v17, v18
	global_store_dwordx2 v[64:65], v[16:17], off offset:176
	v_mul_f32_e32 v2, v15, v66
	v_cvt_pk_bf16_f32 v1, v1, v2
	global_store_dwordx2 v[64:65], v[0:1], off offset:240
	s_load_dwordx8 s[60:67], s[84:85], 0xc8
	v_readfirstlane_b32 s42, v32
	s_ashr_i32 s43, s42, 1
	s_lshl_b32 s20, s35, 8
	s_andn2_b32 s43, s43, 31
	s_add_i32 s43, s43, s20
	s_sub_i32 s52, 0, s53
	s_ashr_i32 s20, s43, 31
	s_add_u32 s56, s2, s43
	s_addc_u32 s59, s3, s20
	s_lshl_b32 s35, s35, 2
	s_waitcnt lgkmcnt(0)
; #define LAS __attribute__((address_space(3)))
; DI int otid() { int t = threadIdx.x; asm volatile("" : "+v"(t)); return t; }
; DI unsigned char* ows(const Params& P) { unsigned char* p = P.ws; asm volatile("" : "+s"(p)); return p; }
; #define ATT_LOAD(kr, vr, t) do { const bf16_t* kp_ = KVb + (size_t)(t) * 64 * 2048 + kn_off; \
;         kr[0] = *(const u32x4*)kp_; kr[1] = *(const u32x4*)(kp_ + 32 * 2048); kr[2] = *(const u32x4*)(KPEb + (t) * 64 * 64 + kp_off); \
;         const bf16_t* vp_ = VTb + (t) * 64 + v_off; vr[0] = *(const u32x4*)vp_; vr[1] = *(const u32x4*)(vp_ + 64 * SEQ); } while (0)
; DI void attn_unit(const Params& P, LAS unsigned char* lds, int b, int h, int qb, bool dry) {
;     const int tid = otid(), lane = tid & 63, w = __builtin_amdgcn_readfirstlane(tid >> 6), r = lane & 31, hh = lane >> 5;
;     bf16_t* Q = (bf16_t*)(ows(P) + OFF_Q);
;     const bf16_t* KV = (const bf16_t*)(ows(P) + OFF_KV); const bf16_t* KPE = (const bf16_t*)(ows(P) + OFF_KPE); const bf16_t* VT = (const bf16_t*)(ows(P) + OFF_U);
;     LAS unsigned char* Ks = lds; LAS unsigned char* Vs = lds + 2 * KS_BYTES;
;     const int q0 = qb * 256 + w * 32;
;     bf16_t* qrow = Q + ((size_t)b * SEQ + q0 + r) * 1536 + h * 192;
;     bf16x8 qf[12];
; #pragma unroll
;     for (int s = 0; s < 12; ++s) qf[s] = *(const bf16x8*)(qrow + 16 * s + 8 * hh);
;     f32x16 o[4];
; #pragma unroll
;     for (int d = 0; d < 4; ++d)
; #pragma unroll
;         for (int i = 0; i < 16; ++i) o[d][i] = 0.f;
;     float mrun = -INFINITY, lrun = 0.f;
;     const int nt = 4 * (qb + 1);
;     const bf16_t* KVb = KV + (size_t)b * SEQ * 2048 + h * 256; const bf16_t* KPEb = KPE + (size_t)b * SEQ * 64; const bf16_t* VTb = VT + (size_t)(b * 8 + h) * 128 * SEQ;
;     const int kn_off = (tid >> 4) * 2048 + (tid & 15) * 8, kn_dst = (tid >> 4) * KS_STRIDE + (tid & 15) * 16;
;     const int kp_off = (tid >> 3) * 64 + (tid & 7) * 8, kp_dst = (tid >> 3) * KS_STRIDE + 256 + (tid & 7) * 16;
;     const int v_off = (tid >> 3) * SEQ + (tid & 7) * 8, v_dst = (tid >> 3) * VS_STRIDE + (tid & 7) * 16;
;     ...
;     u32x4 kA[3], vA[2], kB[3], vB[2];
;     ...
;     ATT_LOAD(kA, vA, 0);
;     __syncthreads();
;     ATT_STORE(kA, vA, 0);
;     ATT_LOAD(kA, vA, 1);
;     __syncthreads();
	s_mov_b64 s[50:51], s[66:67]
	s_mov_b64 s[26:27], s[66:67]
	s_lshl_b32 s20, s36, 1
	s_add_i32 s35, s35, 4
	v_and_b32_e32 v35, 15, v32
	s_add_u32 s2, s26, s44
	v_ashrrev_i32_e32 v34, 4, v32
	v_lshlrev_b32_e32 v0, 3, v35
	v_and_b32_e32 v37, 7, v32
	s_addc_u32 s3, s27, s45
	s_lshl_b32 s36, s37, 1
	v_lshl_or_b32 v0, v34, 11, v0
	v_ashrrev_i32_e32 v36, 3, v32
	v_lshlrev_b32_e32 v1, 3, v37
	s_add_u32 s2, s2, s36
	v_lshl_or_b32 v8, v36, 6, v1
	v_lshl_or_b32 v12, v36, 14, v1
	v_ashrrev_i32_e32 v1, 31, v0
	s_addc_u32 s3, s3, 0
	v_lshlrev_b64 v[20:21], 1, v[0:1]
	s_mov_b64 s[62:63], s[66:67]
	s_mov_b64 s[40:41], s[66:67]
	v_lshl_add_u64 v[22:23], s[2:3], 0, v[20:21]
	s_mov_b32 s2, 0x13808000
	s_add_u32 s36, s40, s46
	v_add_co_u32_e32 v0, vcc, s2, v22
	s_addc_u32 s37, s41, s47
	s_nop 0
	v_addc_co_u32_e32 v1, vcc, 0, v23, vcc
	s_mov_b32 s2, 0x13828000
	v_add_co_u32_e32 v4, vcc, s2, v22
	s_add_u32 s2, s62, s30
	v_ashrrev_i32_e32 v9, 31, v8
	s_addc_u32 s3, s63, s31
	v_addc_co_u32_e32 v5, vcc, 0, v23, vcc
	v_lshl_add_u64 v[24:25], v[8:9], 1, s[2:3]
	s_mov_b32 s2, 0xd408000
	v_ashrrev_i32_e32 v13, 31, v12
	v_add_co_u32_e32 v8, vcc, s2, v24
	v_lshlrev_b64 v[26:27], 1, v[12:13]
	global_load_dwordx4 v[0:3], v[0:1], off
	s_nop 0
	global_load_dwordx4 v[4:7], v[4:5], off
	v_addc_co_u32_e32 v9, vcc, 0, v25, vcc
	v_lshl_add_u64 v[28:29], s[36:37], 0, v[26:27]
	s_mov_b32 s2, 0x5808000
	v_add_co_u32_e32 v12, vcc, s2, v28
	s_mov_b32 s2, 0x5a08000
	s_nop 0
	v_addc_co_u32_e32 v13, vcc, 0, v29, vcc
	v_add_co_u32_e32 v30, vcc, s2, v28
	global_load_dwordx4 v[8:11], v[8:9], off
	s_nop 0
	v_addc_co_u32_e32 v31, vcc, 0, v29, vcc
	global_load_dwordx4 v[12:15], v[12:13], off
	v_and_b32_e32 v38, 31, v32
	global_load_dwordx4 v[16:19], v[30:31], off
	v_bfe_u32 v39, v32, 5, 1
	v_or_b32_e32 v40, s56, v38
	v_mov_b64_e32 v[32:33], s[50:51]
	v_mad_u64_u32 v[32:33], s[2:3], v40, s39, v[32:33]
	v_mad_i32_i24 v33, s59, v248, v33
	v_lshl_add_u64 v[32:33], v[32:33], 0, s[20:21]
	s_mov_b64 s[2:3], 0xd808000
	v_lshl_add_u64 v[186:187], v[32:33], 0, s[2:3]
	v_lshlrev_b32_e32 v184, 4, v39
	v_lshl_add_u64 v[32:33], v[186:187], 0, v[184:185]
	global_load_dwordx4 v[96:99], v[32:33], off
	global_load_dwordx4 v[100:103], v[32:33], off offset:32
	global_load_dwordx4 v[104:107], v[32:33], off offset:64
	global_load_dwordx4 v[108:111], v[32:33], off offset:96
	global_load_dwordx4 v[112:115], v[32:33], off offset:128
	global_load_dwordx4 v[116:119], v[32:33], off offset:160
	global_load_dwordx4 v[120:123], v[32:33], off offset:192
	global_load_dwordx4 v[124:127], v[32:33], off offset:224
	global_load_dwordx4 v[128:131], v[32:33], off offset:256
	global_load_dwordx4 v[132:135], v[32:33], off offset:288
	global_load_dwordx4 v[136:139], v[32:33], off offset:320
	global_load_dwordx4 v[140:143], v[32:33], off offset:352
	v_mul_lo_u32 v32, v34, s29
	v_lshl_add_u32 v33, v35, 4, v32
	v_lshlrev_b32_e32 v32, 4, v37
	v_mad_u64_u32 v[34:35], s[2:3], v36, s68, v[32:33]
	s_mov_b64 s[2:3], 0x5808000
	s_nop 0
	v_lshl_add_u64 v[28:29], v[28:29], 0, s[2:3]
	v_add_u32_e32 v250, 0, v33
	s_movk_i32 s2, 0x108
	s_waitcnt lgkmcnt(0)
	s_barrier
	s_waitcnt vmcnt(0)
	ds_write_b128 v250, v[0:3]
	ds_write_b128 v250, v[4:7] offset:12800
	v_mad_u64_u32 v[0:1], s[2:3], v36, s2, v[34:35]
	s_mov_b32 s2, 0x13848000
	v_add_u32_e32 v251, 0, v0
	v_add_co_u32_e32 v0, vcc, s2, v22
	v_add_u32_e32 v252, 0, v34
	s_nop 0
	v_addc_co_u32_e32 v1, vcc, 0, v23, vcc
	s_mov_b32 s2, 0x13868000
	v_add_u32_e32 v253, 0xc800, v252
	v_add_u32_e32 v254, 0xea00, v252
	v_add_co_u32_e32 v2, vcc, s2, v22
	ds_write_b128 v251, v[8:11] offset:256
	ds_write2_b64 v253, v[12:13], v[14:15] offset1:1
	ds_write2_b64 v254, v[16:17], v[18:19] offset1:1
	v_addc_co_u32_e32 v3, vcc, 0, v23, vcc
	s_mov_b32 s2, 0xd40a000
	global_load_dwordx4 v[144:147], v[0:1], off
	global_load_dwordx4 v[148:151], v[2:3], off
	v_add_co_u32_e32 v0, vcc, s2, v24
	v_mad_u32_u24 v213, v38, s29, 0
	s_nop 0
	v_addc_co_u32_e32 v1, vcc, 0, v25, vcc
	global_load_dwordx4 v[152:155], v[0:1], off
	global_load_dwordx4 v[156:159], v[28:29], off offset:128
	global_load_dwordx4 v[160:163], v[30:31], off offset:128
	s_movk_i32 s2, 0xfef8
	v_mad_i32_i24 v19, v38, s2, v213
	v_mad_u64_u32 v[16:17], s[2:3], v36, s29, v[32:33]
	v_readlane_b32 s2, v246, 47
	s_ashr_i32 s36, s42, 7
	v_lshlrev_b32_e32 v18, 3, v39
	v_mov_b32_e32 v0, s2
	s_mov_b64 s[2:3], 0xd40e000
	v_lshl_add_u64 v[188:189], v[24:25], 0, s[2:3]
	s_add_u32 s2, s40, s48
	s_addc_u32 s3, s41, s49
	v_mad_u32_u24 v17, v38, s68, v0
	v_lshl_add_u64 v[0:1], s[2:3], 0, v[26:27]
	s_mov_b64 s[2:3], 0x5a08180
	v_lshl_add_u64 v[190:191], v[0:1], 0, s[2:3]
	s_add_u32 s2, s26, s57
	s_addc_u32 s3, s27, s58
	v_lshl_add_u64 v[0:1], s[2:3], 0, v[20:21]
	s_mov_b64 s[2:3], 0x138e8000
	v_mov_b32_e32 v14, v185
	v_mov_b32_e32 v15, v185
	v_or_b32_e32 v214, s43, v38
	v_lshlrev_b32_e32 v212, 2, v39
	v_lshl_add_u64 v[192:193], v[0:1], 0, s[2:3]
	s_add_i32 s2, s36, s53
	v_mov_b32_e32 v0, v185
	v_mov_b32_e32 v1, v185
	v_mov_b32_e32 v2, v185
	v_mov_b32_e32 v3, v185
	v_mov_b32_e32 v4, v185
	v_mov_b32_e32 v5, v185
	v_mov_b32_e32 v6, v185
	v_mov_b32_e32 v7, v185
	v_mov_b32_e32 v8, v185
	v_mov_b32_e32 v9, v185
	v_mov_b32_e32 v10, v185
	v_mov_b32_e32 v11, v185
	v_mov_b32_e32 v12, v185
	v_mov_b32_e32 v13, v185
	v_add_u32_e32 v216, v19, v18
	v_add_u32_e32 v217, 0, v16
	v_add_u32_e32 v218, v17, v18
	v_mov_b64_e32 v[30:31], v[14:15]
	v_mov_b64_e32 v[46:47], v[14:15]
	v_mov_b64_e32 v[62:63], v[14:15]
	s_mov_b32 s20, 2
	s_sub_i32 s26, 1, s2
	s_sub_i32 s27, 0, s2
	v_mov_b32_e32 v194, 0xff800000
	v_mov_b32_e32 v196, 0
	v_mov_b32_e32 v197, 0
	v_mov_b32_e32 v198, 0
	v_mov_b32_e32 v199, 0
	v_mov_b32_e32 v200, 0
	v_mov_b32_e32 v201, 0
	v_mov_b32_e32 v202, 0
	v_mov_b32_e32 v203, 0
	v_mov_b32_e32 v204, 0
	v_mov_b32_e32 v205, 0
	v_mov_b32_e32 v206, 0
	v_mov_b32_e32 v207, 0
	v_mov_b32_e32 v208, 0
	v_mov_b32_e32 v209, 0
	v_mov_b32_e32 v210, 0
	v_mov_b32_e32 v211, 0
	v_mov_b32_e32 v215, 0
	v_mov_b32_e32 v219, v212
	v_mov_b64_e32 v[28:29], v[12:13]
	v_mov_b64_e32 v[26:27], v[10:11]
	v_mov_b64_e32 v[24:25], v[8:9]
	v_mov_b64_e32 v[22:23], v[6:7]
	v_mov_b64_e32 v[20:21], v[4:5]
	v_mov_b64_e32 v[18:19], v[2:3]
	v_mov_b64_e32 v[16:17], v[0:1]
	v_mov_b64_e32 v[44:45], v[12:13]
	v_mov_b64_e32 v[42:43], v[10:11]
	v_mov_b64_e32 v[40:41], v[8:9]
	v_mov_b64_e32 v[38:39], v[6:7]
	v_mov_b64_e32 v[36:37], v[4:5]
	v_mov_b64_e32 v[34:35], v[2:3]
	v_mov_b64_e32 v[32:33], v[0:1]
	v_mov_b64_e32 v[60:61], v[12:13]
	v_mov_b64_e32 v[58:59], v[10:11]
	v_mov_b64_e32 v[56:57], v[8:9]
	v_mov_b64_e32 v[54:55], v[6:7]
	v_mov_b64_e32 v[52:53], v[4:5]
	v_mov_b64_e32 v[50:51], v[2:3]
	v_mov_b64_e32 v[48:49], v[0:1]
	s_mov_b64 s[60:61], 0
	s_waitcnt lgkmcnt(0)
	s_barrier
	s_branch .LBB0_53

; #define LAS __attribute__((address_space(3)))
; #define MFMA32(a, b, c) __builtin_amdgcn_mfma_f32_32x32x16_bf16((a), (b), (c), 0, 0, 0)
; DI void attn_unit(const Params& P, LAS unsigned char* lds, int b, int h, int qb, bool dry) {
;     ...
;     auto qk_softmax = [&](int kt, int kslot, bool domask) {
;         const LAS unsigned char* kb_ = Ks + kslot * KS_BYTES + r * KS_STRIDE + 16 * hh;
;         f32x16 s0, s1;
;         __builtin_amdgcn_s_setprio(1);
;         { const f32x16 z16 = {0.f, 0.f, 0.f, 0.f, 0.f, 0.f, 0.f, 0.f, 0.f, 0.f, 0.f, 0.f, 0.f, 0.f, 0.f, 0.f};
;           const bf16x8 a0 = *(const LAS bf16x8*)(kb_), a1 = *(const LAS bf16x8*)(kb_ + 32 * KS_STRIDE);
;           s0 = MFMA32(a0, qf[0], z16); s1 = MFMA32(a1, qf[0], z16); }
; #pragma unroll
;         for (int s = 1; s < 12; ++s) {
;             const bf16x8 a0 = *(const LAS bf16x8*)(kb_ + 32 * s), a1 = *(const LAS bf16x8*)(kb_ + 32 * KS_STRIDE + 32 * s);
;             s0 = MFMA32(a0, qf[s], s0); s1 = MFMA32(a1, qf[s], s1);
;         }
;         __builtin_amdgcn_s_setprio(0);
.LBB0_55:
	s_add_i32 s37, s52, s20
	s_add_i32 s40, s37, -2
	s_cmp_gt_i32 s40, s36
	v_add_u32_e32 v220, v213, v184
	s_cbranch_scc1 .LBB0_61
	s_add_i32 s40, s27, s20
	s_cmp_lg_u32 s40, 2
	s_setprio 1
	ds_read_b128 v[222:225], v220
	ds_read_b128 v[226:229], v220 offset:12800
	ds_read_b128 v[230:233], v220 offset:32
	ds_read_b128 v[234:237], v220 offset:12832
	s_waitcnt lgkmcnt(3)
	v_mfma_f32_32x32x16_bf16 v[80:95], v[222:225], v[96:99], v[196:211]
	ds_read_b128 v[222:225], v220 offset:64
	s_waitcnt lgkmcnt(3)
	v_mfma_f32_32x32x16_bf16 v[64:79], v[226:229], v[96:99], v[196:211]
	ds_read_b128 v[226:229], v220 offset:12864
	s_waitcnt lgkmcnt(3)
	v_mfma_f32_32x32x16_bf16 v[80:95], v[230:233], v[100:103], v[80:95]
	ds_read_b128 v[230:233], v220 offset:96
	s_waitcnt lgkmcnt(3)
	v_mfma_f32_32x32x16_bf16 v[64:79], v[234:237], v[100:103], v[64:79]
	ds_read_b128 v[234:237], v220 offset:12896
	s_waitcnt lgkmcnt(3)
	v_mfma_f32_32x32x16_bf16 v[80:95], v[222:225], v[104:107], v[80:95]
	ds_read_b128 v[222:225], v220 offset:128
	s_waitcnt lgkmcnt(3)
	v_mfma_f32_32x32x16_bf16 v[64:79], v[226:229], v[104:107], v[64:79]
	ds_read_b128 v[226:229], v220 offset:12928
	s_waitcnt lgkmcnt(3)
	v_mfma_f32_32x32x16_bf16 v[80:95], v[230:233], v[108:111], v[80:95]
	ds_read_b128 v[230:233], v220 offset:160
	s_waitcnt lgkmcnt(3)
	v_mfma_f32_32x32x16_bf16 v[64:79], v[234:237], v[108:111], v[64:79]
	ds_read_b128 v[234:237], v220 offset:12960
	s_waitcnt lgkmcnt(3)
	v_mfma_f32_32x32x16_bf16 v[80:95], v[222:225], v[112:115], v[80:95]
	ds_read_b128 v[222:225], v220 offset:192
	s_waitcnt lgkmcnt(3)
	v_mfma_f32_32x32x16_bf16 v[64:79], v[226:229], v[112:115], v[64:79]
	ds_read_b128 v[226:229], v220 offset:12992
	s_waitcnt lgkmcnt(3)
	v_mfma_f32_32x32x16_bf16 v[80:95], v[230:233], v[116:119], v[80:95]
	ds_read_b128 v[230:233], v220 offset:224
	s_waitcnt lgkmcnt(3)
	v_mfma_f32_32x32x16_bf16 v[64:79], v[234:237], v[116:119], v[64:79]
	ds_read_b128 v[234:237], v220 offset:13024
	s_waitcnt lgkmcnt(3)
	v_mfma_f32_32x32x16_bf16 v[80:95], v[222:225], v[120:123], v[80:95]
	ds_read_b128 v[222:225], v220 offset:256
	s_waitcnt lgkmcnt(3)
	v_mfma_f32_32x32x16_bf16 v[64:79], v[226:229], v[120:123], v[64:79]
	ds_read_b128 v[226:229], v220 offset:13056
	s_waitcnt lgkmcnt(3)
	v_mfma_f32_32x32x16_bf16 v[80:95], v[230:233], v[124:127], v[80:95]
	ds_read_b128 v[230:233], v220 offset:288
	s_waitcnt lgkmcnt(3)
	v_mfma_f32_32x32x16_bf16 v[64:79], v[234:237], v[124:127], v[64:79]
	ds_read_b128 v[234:237], v220 offset:13088
	s_waitcnt lgkmcnt(3)
	v_mfma_f32_32x32x16_bf16 v[80:95], v[222:225], v[128:131], v[80:95]
	ds_read_b128 v[222:225], v220 offset:320
	s_waitcnt lgkmcnt(3)
	v_mfma_f32_32x32x16_bf16 v[64:79], v[226:229], v[128:131], v[64:79]
	ds_read_b128 v[226:229], v220 offset:13120
	s_waitcnt lgkmcnt(3)
	v_mfma_f32_32x32x16_bf16 v[80:95], v[230:233], v[132:135], v[80:95]
	ds_read_b128 v[230:233], v220 offset:352
	s_waitcnt lgkmcnt(3)
	v_mfma_f32_32x32x16_bf16 v[64:79], v[234:237], v[132:135], v[64:79]
	ds_read_b128 v[234:237], v220 offset:13152
	s_waitcnt lgkmcnt(3)
	v_mfma_f32_32x32x16_bf16 v[80:95], v[222:225], v[136:139], v[80:95]
	s_waitcnt lgkmcnt(2)
	v_mfma_f32_32x32x16_bf16 v[64:79], v[226:229], v[136:139], v[64:79]
	s_waitcnt lgkmcnt(1)
	v_mfma_f32_32x32x16_bf16 v[80:95], v[230:233], v[140:143], v[80:95]
	s_waitcnt lgkmcnt(0)
	v_mfma_f32_32x32x16_bf16 v[64:79], v[234:237], v[140:143], v[64:79]
	s_setprio 0
	s_nop 0
	s_mov_b64 vcc, s[30:31]
	s_cbranch_vccnz .Lattn_hw2_v5
	s_waitcnt vmcnt(0)
	s_branch .Lattn_hw2_go

; #define LAS __attribute__((address_space(3)))
; #define MFMA32(a, b, c) __builtin_amdgcn_mfma_f32_32x32x16_bf16((a), (b), (c), 0, 0, 0)
; DI void attn_unit(const Params& P, LAS unsigned char* lds, int b, int h, int qb, bool dry) {
;     ...
;     auto qk_softmax = [&](int kt, int kslot, bool domask) {
;         const LAS unsigned char* kb_ = Ks + kslot * KS_BYTES + r * KS_STRIDE + 16 * hh;
;         f32x16 s0, s1;
;         __builtin_amdgcn_s_setprio(1);
;         { const f32x16 z16 = {0.f, 0.f, 0.f, 0.f, 0.f, 0.f, 0.f, 0.f, 0.f, 0.f, 0.f, 0.f, 0.f, 0.f, 0.f, 0.f};
;           const bf16x8 a0 = *(const LAS bf16x8*)(kb_), a1 = *(const LAS bf16x8*)(kb_ + 32 * KS_STRIDE);
;           s0 = MFMA32(a0, qf[0], z16); s1 = MFMA32(a1, qf[0], z16); }
; #pragma unroll
;         for (int s = 1; s < 12; ++s) {
;             const bf16x8 a0 = *(const LAS bf16x8*)(kb_ + 32 * s), a1 = *(const LAS bf16x8*)(kb_ + 32 * KS_STRIDE + 32 * s);
;             s0 = MFMA32(a0, qf[s], s0); s1 = MFMA32(a1, qf[s], s1);
;         }
;         __builtin_amdgcn_s_setprio(0);
.LBB0_65:
	s_add_i32 s30, s26, s20
	s_cmp_lg_u32 s30, 2
	s_setprio 1
	ds_read_b128 v[222:225], v220 offset:25600
	ds_read_b128 v[226:229], v220 offset:38400
	ds_read_b128 v[230:233], v220 offset:25632
	ds_read_b128 v[234:237], v220 offset:38432
	s_waitcnt lgkmcnt(3)
	v_mfma_f32_32x32x16_bf16 v[80:95], v[222:225], v[96:99], v[196:211]
	ds_read_b128 v[222:225], v220 offset:25664
	s_waitcnt lgkmcnt(3)
	v_mfma_f32_32x32x16_bf16 v[64:79], v[226:229], v[96:99], v[196:211]
	ds_read_b128 v[226:229], v220 offset:38464
	s_waitcnt lgkmcnt(3)
	v_mfma_f32_32x32x16_bf16 v[80:95], v[230:233], v[100:103], v[80:95]
	ds_read_b128 v[230:233], v220 offset:25696
	s_waitcnt lgkmcnt(3)
	v_mfma_f32_32x32x16_bf16 v[64:79], v[234:237], v[100:103], v[64:79]
	ds_read_b128 v[234:237], v220 offset:38496
	s_waitcnt lgkmcnt(3)
	v_mfma_f32_32x32x16_bf16 v[80:95], v[222:225], v[104:107], v[80:95]
	ds_read_b128 v[222:225], v220 offset:25728
	s_waitcnt lgkmcnt(3)
	v_mfma_f32_32x32x16_bf16 v[64:79], v[226:229], v[104:107], v[64:79]
	ds_read_b128 v[226:229], v220 offset:38528
	s_waitcnt lgkmcnt(3)
	v_mfma_f32_32x32x16_bf16 v[80:95], v[230:233], v[108:111], v[80:95]
	ds_read_b128 v[230:233], v220 offset:25760
	s_waitcnt lgkmcnt(3)
	v_mfma_f32_32x32x16_bf16 v[64:79], v[234:237], v[108:111], v[64:79]
	ds_read_b128 v[234:237], v220 offset:38560
	s_waitcnt lgkmcnt(3)
	v_mfma_f32_32x32x16_bf16 v[80:95], v[222:225], v[112:115], v[80:95]
	ds_read_b128 v[222:225], v220 offset:25792
	s_waitcnt lgkmcnt(3)
	v_mfma_f32_32x32x16_bf16 v[64:79], v[226:229], v[112:115], v[64:79]
	ds_read_b128 v[226:229], v220 offset:38592
	s_waitcnt lgkmcnt(3)
	v_mfma_f32_32x32x16_bf16 v[80:95], v[230:233], v[116:119], v[80:95]
	ds_read_b128 v[230:233], v220 offset:25824
	s_waitcnt lgkmcnt(3)
	v_mfma_f32_32x32x16_bf16 v[64:79], v[234:237], v[116:119], v[64:79]
	ds_read_b128 v[234:237], v220 offset:38624
	s_waitcnt lgkmcnt(3)
	v_mfma_f32_32x32x16_bf16 v[80:95], v[222:225], v[120:123], v[80:95]
	ds_read_b128 v[222:225], v220 offset:25856
	s_waitcnt lgkmcnt(3)
	v_mfma_f32_32x32x16_bf16 v[64:79], v[226:229], v[120:123], v[64:79]
	ds_read_b128 v[226:229], v220 offset:38656
	s_waitcnt lgkmcnt(3)
	v_mfma_f32_32x32x16_bf16 v[80:95], v[230:233], v[124:127], v[80:95]
	ds_read_b128 v[230:233], v220 offset:25888
	s_waitcnt lgkmcnt(3)
	v_mfma_f32_32x32x16_bf16 v[64:79], v[234:237], v[124:127], v[64:79]
	ds_read_b128 v[234:237], v220 offset:38688
	s_waitcnt lgkmcnt(3)
	v_mfma_f32_32x32x16_bf16 v[80:95], v[222:225], v[128:131], v[80:95]
	ds_read_b128 v[222:225], v220 offset:25920
	s_waitcnt lgkmcnt(3)
	v_mfma_f32_32x32x16_bf16 v[64:79], v[226:229], v[128:131], v[64:79]
	ds_read_b128 v[226:229], v220 offset:38720
	s_waitcnt lgkmcnt(3)
	v_mfma_f32_32x32x16_bf16 v[80:95], v[230:233], v[132:135], v[80:95]
	ds_read_b128 v[230:233], v220 offset:25952
	s_waitcnt lgkmcnt(3)
	v_mfma_f32_32x32x16_bf16 v[64:79], v[234:237], v[132:135], v[64:79]
	ds_read_b128 v[234:237], v220 offset:38752
	s_waitcnt lgkmcnt(3)
	v_mfma_f32_32x32x16_bf16 v[80:95], v[222:225], v[136:139], v[80:95]
	s_waitcnt lgkmcnt(2)
	v_mfma_f32_32x32x16_bf16 v[64:79], v[226:229], v[136:139], v[64:79]
	s_waitcnt lgkmcnt(1)
	v_mfma_f32_32x32x16_bf16 v[80:95], v[230:233], v[140:143], v[80:95]
	s_waitcnt lgkmcnt(0)
	v_mfma_f32_32x32x16_bf16 v[64:79], v[234:237], v[140:143], v[64:79]
	s_setprio 0
	s_nop 0
	s_mov_b64 vcc, s[40:41]
	s_cbranch_vccnz .Lattn_hw3_skip
	s_waitcnt vmcnt(5)
	ds_write_b128 v250, v[164:167]
	ds_write_b128 v250, v[168:171] offset:12800
	ds_write_b128 v251, v[172:175] offset:256
	ds_write2_b64 v253, v[176:177], v[178:179] offset1:1
	ds_write2_b64 v254, v[180:181], v[182:183] offset1:1

; #define LAS __attribute__((address_space(3)))
; DI int obid() { int b = blockIdx.x; asm volatile("" : "+s"(b)); return b; }
; DI void phase_attn(const Params& P, LAS unsigned char* lds, bool dry) {
;     for (int item = obid(); item < 512; item += gridDim.x) {
;         const int h = item & 7, p = (item >> 3) & 31, b = item >> 8;
;         attn_unit(P, lds, b, h, 63 - p, dry);
;         attn_unit(P, lds, b, h, p, dry);
;     }
; }
.LBB0_71:
	s_mov_b64 s[48:49], 0
	v_mov_b32_e32 v196, 0x12000
	v_mov_b32_e32 v197, 0x1b000
	v_mov_b32_e32 v198, 0x3727c5ac
	v_mov_b32_e32 v199, 0x260
	v_mov_b32_e32 v200, 1
	v_mov_b32_e32 v201, 0xc00
	v_mov_b32_e32 v202, 0xff800000
	v_mov_b32_e32 v203, 0x9000
	v_mov_b32_e32 v204, 0x2900
	v_mov_b32_e32 v205, 0x41b17218
	v_mov_b32_e32 v206, 0xffffc000
	v_readlane_b32 s29, v246, 59
	v_readlane_b32 s70, v246, 60
	s_movk_i32 s20, 0x7fff
	s_mov_b32 s96, 0x1c000
	s_mov_b32 s97, 0x21000
	s_movk_i32 s99, 0x5000

; __global__ void __launch_bounds__(NTHR) fwd_megakernel(Params P) {
	.amdhsa_kernel _Z14fwd_megakernel6Params
		.amdhsa_group_segment_fixed_size 0
		.amdhsa_private_segment_fixed_size 0
		.amdhsa_kernarg_size 488
		.amdhsa_user_sgpr_count 2
		.amdhsa_user_sgpr_dispatch_ptr 0
		.amdhsa_user_sgpr_queue_ptr 0
		.amdhsa_user_sgpr_kernarg_segment_ptr 1
		.amdhsa_user_sgpr_dispatch_id 0
		.amdhsa_user_sgpr_kernarg_preload_length 0
		.amdhsa_user_sgpr_kernarg_preload_offset 0
		.amdhsa_user_sgpr_private_segment_size 0
		.amdhsa_uses_dynamic_stack 0
		.amdhsa_enable_private_segment 0
		.amdhsa_system_sgpr_workgroup_id_x 1
		.amdhsa_system_sgpr_workgroup_id_y 0
		.amdhsa_system_sgpr_workgroup_id_z 0
		.amdhsa_system_sgpr_workgroup_info 0
		.amdhsa_system_vgpr_workitem_id 2
		.amdhsa_next_free_vgpr 256
		.amdhsa_next_free_sgpr 102
		.amdhsa_accum_offset 256
		.amdhsa_reserve_vcc 1
		.amdhsa_float_round_mode_32 0
		.amdhsa_float_round_mode_16_64 0
		.amdhsa_float_denorm_mode_32 3
		.amdhsa_float_denorm_mode_16_64 3
		.amdhsa_dx10_clamp 1
		.amdhsa_ieee_mode 1
		.amdhsa_fp16_overflow 0
		.amdhsa_tg_split 0
		.amdhsa_exception_fp_ieee_invalid_op 0
		.amdhsa_exception_fp_denorm_src 0
		.amdhsa_exception_fp_ieee_div_zero 0
		.amdhsa_exception_fp_ieee_overflow 0
		.amdhsa_exception_fp_ieee_underflow 0
		.amdhsa_exception_fp_ieee_inexact 0
		.amdhsa_exception_int_div_zero 0
	.end_amdhsa_kernel

; __global__ void __launch_bounds__(NTHR) fwd_megakernel(Params P) {
amdhsa.kernels:
  - .agpr_count:     0
    .args:
      - .offset:         0
        .size:           232
        .value_kind:     by_value
      - .offset:         232
        .size:           4
        .value_kind:     hidden_block_count_x
      - .offset:         236
        .size:           4
        .value_kind:     hidden_block_count_y
      - .offset:         240
        .size:           4
        .value_kind:     hidden_block_count_z
      - .offset:         244
        .size:           2
        .value_kind:     hidden_group_size_x
      - .offset:         246
        .size:           2
        .value_kind:     hidden_group_size_y
      - .offset:         248
        .size:           2
        .value_kind:     hidden_group_size_z
      - .offset:         250
        .size:           2
        .value_kind:     hidden_remainder_x
      - .offset:         252
        .size:           2
        .value_kind:     hidden_remainder_y
      - .offset:         254
        .size:           2
        .value_kind:     hidden_remainder_z
      - .offset:         272
        .size:           8
        .value_kind:     hidden_global_offset_x
      - .offset:         280
        .size:           8
        .value_kind:     hidden_global_offset_y
      - .offset:         288
        .size:           8
        .value_kind:     hidden_global_offset_z
      - .offset:         296
        .size:           2
        .value_kind:     hidden_grid_dims
      - .offset:         320
        .size:           8
        .value_kind:     hidden_multigrid_sync_arg
      - .offset:         352
        .size:           4
        .value_kind:     hidden_dynamic_lds_size
    .group_segment_fixed_size: 0
    .kernarg_segment_align: 8
    .kernarg_segment_size: 488
    .language:       OpenCL C
    .language_version:
      - 2
      - 0
    .max_flat_workgroup_size: 512
    .name:           _Z14fwd_megakernel6Params
    .private_segment_fixed_size: 0
    .sgpr_count:     108
    .sgpr_spill_count: 168
    .symbol:         _Z14fwd_megakernel6Params.kd
    .uniform_work_group_size: 1
    .uses_dynamic_stack: false
    .vgpr_count:     256
    .vgpr_spill_count: 0
    .wavefront_size: 64
